# redundant_post_barrier_lgkmcnt_removed_24_sites
# speedup vs baseline: 1.0049x; 1.0049x over previous
.LBB0_220:
	s_add_u32 s50, s14, 0x100
	s_addc_u32 s51, s15, 0
	s_and_b64 s[52:53], s[52:53], exec
	s_cselect_b32 s55, s58, s51
	s_cselect_b32 s54, s59, s50
	s_cselect_b32 s53, s43, s80
	s_cselect_b32 s52, s77, s79
	s_add_i32 s82, 0, 0x10000
	v_add_u32_e32 v0, s82, v187
	s_add_i32 s83, 0, 0x14000
	ds_read_b128 v[130:133], v0
	ds_read_b128 v[134:137], v0 offset:1024
	ds_read_b128 v[176:179], v0 offset:2048
	ds_read_b128 v[180:183], v0 offset:3072
	v_add_u32_e32 v0, s83, v187
	ds_read_b128 v[192:195], v0
	ds_read_b128 v[196:199], v0 offset:1024
	ds_read_b128 v[200:203], v0 offset:2048
	ds_read_b128 v[204:207], v0 offset:3072
	v_lshl_add_u64 v[184:185], s[14:15], 0, v[172:173]
	s_add_i32 m0, s66, 0xc000
	ds_read_b128 v[208:211], v190
	ds_read_b128 v[212:215], v190 offset:1024
	ds_read_b128 v[226:229], v190 offset:2048
	ds_read_b128 v[230:233], v190 offset:3072
	ds_read_b128 v[234:237], v190 offset:4096
	ds_read_b128 v[238:241], v190 offset:5120
	ds_read_b128 v[242:245], v190 offset:6144
	ds_read_b128 v[246:249], v190 offset:7168
	global_load_lds_dwordx4 v[184:185], off
	v_lshl_add_u64 v[184:185], s[14:15], 0, v[174:175]
	s_add_i32 m0, s66, 0xe000
	s_nop 0
	global_load_lds_dwordx4 v[184:185], off
	s_waitcnt vmcnt(8)
	s_waitcnt lgkmcnt(0)
	s_barrier
	s_setprio 1
	v_mfma_f32_16x16x32_bf16 v[126:129], v[130:133], v[208:211], v[126:129]
	v_mfma_f32_16x16x32_bf16 v[122:125], v[176:179], v[208:211], v[122:125]
	v_mfma_f32_16x16x32_bf16 v[110:113], v[130:133], v[226:229], v[110:113]
	v_mfma_f32_16x16x32_bf16 v[106:109], v[176:179], v[226:229], v[106:109]
	v_mfma_f32_16x16x32_bf16 v[94:97], v[130:133], v[234:237], v[94:97]
	v_mfma_f32_16x16x32_bf16 v[90:93], v[176:179], v[234:237], v[90:93]
	v_mfma_f32_16x16x32_bf16 v[78:81], v[130:133], v[242:245], v[78:81]
	v_mfma_f32_16x16x32_bf16 v[74:77], v[176:179], v[242:245], v[74:77]
	v_mfma_f32_16x16x32_bf16 v[126:129], v[134:137], v[212:215], v[126:129]
	v_mfma_f32_16x16x32_bf16 v[122:125], v[180:183], v[212:215], v[122:125]
	v_mfma_f32_16x16x32_bf16 v[110:113], v[134:137], v[230:233], v[110:113]
	v_mfma_f32_16x16x32_bf16 v[106:109], v[180:183], v[230:233], v[106:109]
	v_mfma_f32_16x16x32_bf16 v[94:97], v[134:137], v[238:241], v[94:97]
	v_mfma_f32_16x16x32_bf16 v[90:93], v[180:183], v[238:241], v[90:93]
	v_mfma_f32_16x16x32_bf16 v[78:81], v[134:137], v[246:249], v[78:81]
	v_mfma_f32_16x16x32_bf16 v[74:77], v[180:183], v[246:249], v[74:77]
	s_setprio 0
	s_setprio 1
	v_mfma_f32_16x16x32_bf16 v[118:121], v[192:195], v[208:211], v[118:121]
	v_mfma_f32_16x16x32_bf16 v[114:117], v[200:203], v[208:211], v[114:117]
	v_mfma_f32_16x16x32_bf16 v[102:105], v[192:195], v[226:229], v[102:105]
	v_mfma_f32_16x16x32_bf16 v[98:101], v[200:203], v[226:229], v[98:101]
	v_mfma_f32_16x16x32_bf16 v[86:89], v[192:195], v[234:237], v[86:89]
	v_mfma_f32_16x16x32_bf16 v[82:85], v[200:203], v[234:237], v[82:85]
	v_mfma_f32_16x16x32_bf16 v[70:73], v[192:195], v[242:245], v[70:73]
	v_mfma_f32_16x16x32_bf16 v[66:69], v[200:203], v[242:245], v[66:69]
	v_mfma_f32_16x16x32_bf16 v[118:121], v[196:199], v[212:215], v[118:121]
	v_mfma_f32_16x16x32_bf16 v[114:117], v[204:207], v[212:215], v[114:117]
	v_mfma_f32_16x16x32_bf16 v[102:105], v[196:199], v[230:233], v[102:105]
	v_mfma_f32_16x16x32_bf16 v[98:101], v[204:207], v[230:233], v[98:101]
	v_mfma_f32_16x16x32_bf16 v[86:89], v[196:199], v[238:241], v[86:89]
	v_mfma_f32_16x16x32_bf16 v[82:85], v[204:207], v[238:241], v[82:85]
	v_mfma_f32_16x16x32_bf16 v[70:73], v[196:199], v[246:249], v[70:73]
	v_mfma_f32_16x16x32_bf16 v[66:69], v[204:207], v[246:249], v[66:69]
	s_setprio 0
	s_barrier
	s_add_i32 s14, s82, s65
	v_lshl_add_u64 v[184:185], s[52:53], 0, v[140:141]
	s_mov_b32 m0, s14
	ds_read_b128 v[208:211], v190 offset:16384
	ds_read_b128 v[212:215], v190 offset:17408
	ds_read_b128 v[226:229], v190 offset:18432
	ds_read_b128 v[230:233], v190 offset:19456
	ds_read_b128 v[234:237], v190 offset:20480
	ds_read_b128 v[238:241], v190 offset:21504
	ds_read_b128 v[242:245], v190 offset:22528
	ds_read_b128 v[246:249], v190 offset:23552
	global_load_lds_dwordx4 v[184:185], off
	s_add_i32 m0, s14, 0x2000
	s_add_u32 s14, s52, 0x40000
	v_lshl_add_u64 v[216:217], s[52:53], 0, v[144:145]
	s_addc_u32 s15, s53, 0
	s_add_i32 s82, s83, s65
	global_load_lds_dwordx4 v[216:217], off
	v_lshl_add_u64 v[218:219], s[14:15], 0, v[140:141]
	s_mov_b32 m0, s82
	v_lshl_add_u64 v[220:221], s[54:55], 0, v[142:143]
	global_load_lds_dwordx4 v[218:219], off
	v_lshl_add_u64 v[218:219], s[14:15], 0, v[144:145]
	s_add_i32 m0, s82, 0x2000
	s_nop 0
	global_load_lds_dwordx4 v[218:219], off
	v_lshl_add_u64 v[218:219], s[54:55], 0, v[138:139]
	s_mov_b32 m0, s66
	s_nop 0
	global_load_lds_dwordx4 v[218:219], off
	s_mov_b32 m0, s67
	s_nop 0
	global_load_lds_dwordx4 v[220:221], off
	s_waitcnt vmcnt(8)
	s_waitcnt lgkmcnt(0)
	s_barrier
	s_setprio 1
	v_mfma_f32_16x16x32_bf16 v[62:65], v[130:133], v[208:211], v[62:65]
	v_mfma_f32_16x16x32_bf16 v[58:61], v[176:179], v[208:211], v[58:61]
	v_mfma_f32_16x16x32_bf16 v[46:49], v[130:133], v[226:229], v[46:49]
	v_mfma_f32_16x16x32_bf16 v[42:45], v[176:179], v[226:229], v[42:45]
	v_mfma_f32_16x16x32_bf16 v[30:33], v[130:133], v[234:237], v[30:33]
	v_mfma_f32_16x16x32_bf16 v[26:29], v[176:179], v[234:237], v[26:29]
	v_mfma_f32_16x16x32_bf16 v[14:17], v[130:133], v[242:245], v[14:17]
	v_mfma_f32_16x16x32_bf16 v[10:13], v[176:179], v[242:245], v[10:13]
	v_mfma_f32_16x16x32_bf16 v[62:65], v[134:137], v[212:215], v[62:65]
	v_mfma_f32_16x16x32_bf16 v[58:61], v[180:183], v[212:215], v[58:61]
	v_mfma_f32_16x16x32_bf16 v[46:49], v[134:137], v[230:233], v[46:49]
	v_mfma_f32_16x16x32_bf16 v[42:45], v[180:183], v[230:233], v[42:45]
	v_mfma_f32_16x16x32_bf16 v[30:33], v[134:137], v[238:241], v[30:33]
	v_mfma_f32_16x16x32_bf16 v[26:29], v[180:183], v[238:241], v[26:29]
	v_mfma_f32_16x16x32_bf16 v[14:17], v[134:137], v[246:249], v[14:17]
	v_mfma_f32_16x16x32_bf16 v[10:13], v[180:183], v[246:249], v[10:13]
	s_setprio 0
	s_setprio 1
	v_mfma_f32_16x16x32_bf16 v[54:57], v[192:195], v[208:211], v[54:57]
	v_mfma_f32_16x16x32_bf16 v[50:53], v[200:203], v[208:211], v[50:53]
	v_mfma_f32_16x16x32_bf16 v[38:41], v[192:195], v[226:229], v[38:41]
	v_mfma_f32_16x16x32_bf16 v[34:37], v[200:203], v[226:229], v[34:37]
	v_mfma_f32_16x16x32_bf16 v[22:25], v[192:195], v[234:237], v[22:25]
	v_mfma_f32_16x16x32_bf16 v[18:21], v[200:203], v[234:237], v[18:21]
	v_mfma_f32_16x16x32_bf16 v[6:9], v[192:195], v[242:245], v[6:9]
	v_mfma_f32_16x16x32_bf16 v[2:5], v[200:203], v[242:245], v[2:5]
	v_mfma_f32_16x16x32_bf16 v[54:57], v[196:199], v[212:215], v[54:57]
	v_mfma_f32_16x16x32_bf16 v[50:53], v[204:207], v[212:215], v[50:53]
	v_mfma_f32_16x16x32_bf16 v[38:41], v[196:199], v[230:233], v[38:41]
	v_mfma_f32_16x16x32_bf16 v[34:37], v[204:207], v[230:233], v[34:37]
	v_mfma_f32_16x16x32_bf16 v[22:25], v[196:199], v[238:241], v[22:25]
	v_mfma_f32_16x16x32_bf16 v[18:21], v[204:207], v[238:241], v[18:21]
	v_mfma_f32_16x16x32_bf16 v[6:9], v[196:199], v[246:249], v[6:9]
	v_mfma_f32_16x16x32_bf16 v[2:5], v[204:207], v[246:249], v[2:5]
	s_setprio 0
	s_barrier
	s_add_i32 s82, 0, 0x18000
	v_add_u32_e32 v0, s82, v187
	s_add_i32 s83, 0, 0x1c000
	ds_read_b128 v[130:133], v0
	ds_read_b128 v[134:137], v0 offset:1024
	ds_read_b128 v[176:179], v0 offset:2048
	ds_read_b128 v[180:183], v0 offset:3072
	v_add_u32_e32 v0, s83, v187
	ds_read_b128 v[192:195], v0
	ds_read_b128 v[196:199], v0 offset:1024
	ds_read_b128 v[200:203], v0 offset:2048
	ds_read_b128 v[204:207], v0 offset:3072
	s_add_u32 s14, s54, 0x40000
	s_addc_u32 s15, s55, 0
	s_mov_b32 m0, s68
	v_lshl_add_u64 v[250:251], s[14:15], 0, v[138:139]
	ds_read_b128 v[208:211], v190 offset:32768
	ds_read_b128 v[212:215], v190 offset:33792
	ds_read_b128 v[226:229], v190 offset:34816
	ds_read_b128 v[230:233], v190 offset:35840
	ds_read_b128 v[234:237], v190 offset:36864
	ds_read_b128 v[238:241], v190 offset:37888
	ds_read_b128 v[242:245], v190 offset:38912
	ds_read_b128 v[246:249], v190 offset:39936
	global_load_lds_dwordx4 v[250:251], off
	v_lshl_add_u64 v[250:251], s[14:15], 0, v[142:143]
	s_mov_b32 m0, s69
	s_nop 0
	global_load_lds_dwordx4 v[250:251], off
	s_waitcnt vmcnt(8)
	s_waitcnt lgkmcnt(0)
	s_barrier
	s_setprio 1
	v_mfma_f32_16x16x32_bf16 v[126:129], v[130:133], v[208:211], v[126:129]
	v_mfma_f32_16x16x32_bf16 v[122:125], v[176:179], v[208:211], v[122:125]
	v_mfma_f32_16x16x32_bf16 v[110:113], v[130:133], v[226:229], v[110:113]
	v_mfma_f32_16x16x32_bf16 v[106:109], v[176:179], v[226:229], v[106:109]
	v_mfma_f32_16x16x32_bf16 v[94:97], v[130:133], v[234:237], v[94:97]
	v_mfma_f32_16x16x32_bf16 v[90:93], v[176:179], v[234:237], v[90:93]
	v_mfma_f32_16x16x32_bf16 v[78:81], v[130:133], v[242:245], v[78:81]
	v_mfma_f32_16x16x32_bf16 v[74:77], v[176:179], v[242:245], v[74:77]
	v_mfma_f32_16x16x32_bf16 v[126:129], v[134:137], v[212:215], v[126:129]
	v_mfma_f32_16x16x32_bf16 v[122:125], v[180:183], v[212:215], v[122:125]
	v_mfma_f32_16x16x32_bf16 v[110:113], v[134:137], v[230:233], v[110:113]
	v_mfma_f32_16x16x32_bf16 v[106:109], v[180:183], v[230:233], v[106:109]
	v_mfma_f32_16x16x32_bf16 v[94:97], v[134:137], v[238:241], v[94:97]
	v_mfma_f32_16x16x32_bf16 v[90:93], v[180:183], v[238:241], v[90:93]
	v_mfma_f32_16x16x32_bf16 v[78:81], v[134:137], v[246:249], v[78:81]
	v_mfma_f32_16x16x32_bf16 v[74:77], v[180:183], v[246:249], v[74:77]
	s_setprio 0
	s_setprio 1
	v_mfma_f32_16x16x32_bf16 v[118:121], v[192:195], v[208:211], v[118:121]
	v_mfma_f32_16x16x32_bf16 v[114:117], v[200:203], v[208:211], v[114:117]
	v_mfma_f32_16x16x32_bf16 v[102:105], v[192:195], v[226:229], v[102:105]
	v_mfma_f32_16x16x32_bf16 v[98:101], v[200:203], v[226:229], v[98:101]
	v_mfma_f32_16x16x32_bf16 v[86:89], v[192:195], v[234:237], v[86:89]
	v_mfma_f32_16x16x32_bf16 v[82:85], v[200:203], v[234:237], v[82:85]
	v_mfma_f32_16x16x32_bf16 v[70:73], v[192:195], v[242:245], v[70:73]
	v_mfma_f32_16x16x32_bf16 v[66:69], v[200:203], v[242:245], v[66:69]
	v_mfma_f32_16x16x32_bf16 v[118:121], v[196:199], v[212:215], v[118:121]
	v_mfma_f32_16x16x32_bf16 v[114:117], v[204:207], v[212:215], v[114:117]
	v_mfma_f32_16x16x32_bf16 v[102:105], v[196:199], v[230:233], v[102:105]
	v_mfma_f32_16x16x32_bf16 v[98:101], v[204:207], v[230:233], v[98:101]
	v_mfma_f32_16x16x32_bf16 v[86:89], v[196:199], v[238:241], v[86:89]
	v_mfma_f32_16x16x32_bf16 v[82:85], v[204:207], v[238:241], v[82:85]
	v_mfma_f32_16x16x32_bf16 v[70:73], v[196:199], v[246:249], v[70:73]
	v_mfma_f32_16x16x32_bf16 v[66:69], v[204:207], v[246:249], v[66:69]
	s_setprio 0
	s_barrier
	s_mov_b64 s[54:55], 0x80
	s_add_i32 s14, s82, s65
	v_lshl_add_u64 v[184:185], v[184:185], 0, s[54:55]
	s_mov_b32 m0, s14
	ds_read_b128 v[208:211], v190 offset:49152
	ds_read_b128 v[212:215], v190 offset:50176
	ds_read_b128 v[226:229], v190 offset:51200
	ds_read_b128 v[230:233], v190 offset:52224
	ds_read_b128 v[234:237], v190 offset:53248
	ds_read_b128 v[238:241], v190 offset:54272
	ds_read_b128 v[242:245], v190 offset:55296
	ds_read_b128 v[246:249], v190 offset:56320
	global_load_lds_dwordx4 v[184:185], off
	s_add_i32 m0, s14, 0x2000
	s_add_u32 s14, s52, 0x40080
	v_lshl_add_u64 v[184:185], v[216:217], 0, s[54:55]
	s_addc_u32 s15, s53, 0
	s_add_i32 s52, s83, s65
	global_load_lds_dwordx4 v[184:185], off
	v_lshl_add_u64 v[184:185], s[14:15], 0, v[140:141]
	s_mov_b32 m0, s52
	s_mov_b64 s[82:83], 0x80
	global_load_lds_dwordx4 v[184:185], off
	v_lshl_add_u64 v[184:185], s[14:15], 0, v[144:145]
	s_add_i32 m0, s52, 0x2000
	s_nop 0
	global_load_lds_dwordx4 v[184:185], off
	v_lshl_add_u64 v[184:185], v[218:219], 0, s[82:83]
	s_mov_b32 m0, s71
	s_nop 0
	global_load_lds_dwordx4 v[184:185], off
	v_lshl_add_u64 v[184:185], v[220:221], 0, s[82:83]
	s_mov_b32 m0, s74
	s_nop 0
	global_load_lds_dwordx4 v[184:185], off
	s_waitcnt vmcnt(8)
	s_waitcnt lgkmcnt(0)
	s_barrier
	s_setprio 1
	v_mfma_f32_16x16x32_bf16 v[62:65], v[130:133], v[208:211], v[62:65]
	v_mfma_f32_16x16x32_bf16 v[58:61], v[176:179], v[208:211], v[58:61]
	v_mfma_f32_16x16x32_bf16 v[46:49], v[130:133], v[226:229], v[46:49]
	v_mfma_f32_16x16x32_bf16 v[42:45], v[176:179], v[226:229], v[42:45]
	v_mfma_f32_16x16x32_bf16 v[30:33], v[130:133], v[234:237], v[30:33]
	v_mfma_f32_16x16x32_bf16 v[26:29], v[176:179], v[234:237], v[26:29]
	v_mfma_f32_16x16x32_bf16 v[14:17], v[130:133], v[242:245], v[14:17]
	v_mfma_f32_16x16x32_bf16 v[10:13], v[176:179], v[242:245], v[10:13]
	v_mfma_f32_16x16x32_bf16 v[62:65], v[134:137], v[212:215], v[62:65]
	v_mfma_f32_16x16x32_bf16 v[58:61], v[180:183], v[212:215], v[58:61]
	v_mfma_f32_16x16x32_bf16 v[46:49], v[134:137], v[230:233], v[46:49]
	v_mfma_f32_16x16x32_bf16 v[42:45], v[180:183], v[230:233], v[42:45]
	v_mfma_f32_16x16x32_bf16 v[30:33], v[134:137], v[238:241], v[30:33]
	v_mfma_f32_16x16x32_bf16 v[26:29], v[180:183], v[238:241], v[26:29]
	v_mfma_f32_16x16x32_bf16 v[14:17], v[134:137], v[246:249], v[14:17]
	v_mfma_f32_16x16x32_bf16 v[10:13], v[180:183], v[246:249], v[10:13]
	s_setprio 0
	s_setprio 1
	v_mfma_f32_16x16x32_bf16 v[54:57], v[192:195], v[208:211], v[54:57]
	v_mfma_f32_16x16x32_bf16 v[50:53], v[200:203], v[208:211], v[50:53]
	v_mfma_f32_16x16x32_bf16 v[38:41], v[192:195], v[226:229], v[38:41]
	v_mfma_f32_16x16x32_bf16 v[34:37], v[200:203], v[226:229], v[34:37]
	v_mfma_f32_16x16x32_bf16 v[22:25], v[192:195], v[234:237], v[22:25]
	v_mfma_f32_16x16x32_bf16 v[18:21], v[200:203], v[234:237], v[18:21]
	v_mfma_f32_16x16x32_bf16 v[6:9], v[192:195], v[242:245], v[6:9]
	v_mfma_f32_16x16x32_bf16 v[2:5], v[200:203], v[242:245], v[2:5]
	v_mfma_f32_16x16x32_bf16 v[54:57], v[196:199], v[212:215], v[54:57]
	v_mfma_f32_16x16x32_bf16 v[50:53], v[204:207], v[212:215], v[50:53]
	v_mfma_f32_16x16x32_bf16 v[38:41], v[196:199], v[230:233], v[38:41]
	v_mfma_f32_16x16x32_bf16 v[34:37], v[204:207], v[230:233], v[34:37]
	v_mfma_f32_16x16x32_bf16 v[22:25], v[196:199], v[238:241], v[22:25]
	v_mfma_f32_16x16x32_bf16 v[18:21], v[204:207], v[238:241], v[18:21]
	v_mfma_f32_16x16x32_bf16 v[6:9], v[196:199], v[246:249], v[6:9]
	v_mfma_f32_16x16x32_bf16 v[2:5], v[204:207], v[246:249], v[2:5]
	s_setprio 0
	s_barrier
	s_add_i32 s81, s81, 2
	s_add_u32 s79, s79, 0x100
	s_addc_u32 s80, s80, 0
	s_cmp_gt_u32 s81, 13
	s_cbranch_scc1 .LBB0_222
	s_mov_b64 s[14:15], s[50:51]
	s_branch .LBB0_216

.LBB0_329:
	s_add_u32 s48, s14, 0x100
	s_addc_u32 s49, s15, 0
	s_and_b64 s[50:51], s[50:51], exec
	s_cselect_b32 s53, s56, s49
	s_cselect_b32 s52, s57, s48
	s_cselect_b32 s51, s41, s76
	s_cselect_b32 s50, s71, s75
	s_add_i32 s78, 0, 0x10000
	v_add_u32_e32 v0, s78, v187
	s_add_i32 s79, 0, 0x14000
	ds_read_b128 v[130:133], v0
	ds_read_b128 v[134:137], v0 offset:1024
	ds_read_b128 v[176:179], v0 offset:2048
	ds_read_b128 v[180:183], v0 offset:3072
	v_add_u32_e32 v0, s79, v187
	ds_read_b128 v[192:195], v0
	ds_read_b128 v[196:199], v0 offset:1024
	ds_read_b128 v[200:203], v0 offset:2048
	ds_read_b128 v[204:207], v0 offset:3072
	v_lshl_add_u64 v[184:185], s[14:15], 0, v[172:173]
	s_add_i32 m0, s62, 0xc000
	ds_read_b128 v[208:211], v190
	ds_read_b128 v[212:215], v190 offset:1024
	ds_read_b128 v[226:229], v190 offset:2048
	ds_read_b128 v[230:233], v190 offset:3072
	ds_read_b128 v[234:237], v190 offset:4096
	ds_read_b128 v[238:241], v190 offset:5120
	ds_read_b128 v[242:245], v190 offset:6144
	ds_read_b128 v[246:249], v190 offset:7168
	global_load_lds_dwordx4 v[184:185], off
	v_lshl_add_u64 v[184:185], s[14:15], 0, v[174:175]
	s_add_i32 m0, s62, 0xe000
	s_nop 0
	global_load_lds_dwordx4 v[184:185], off
	s_waitcnt vmcnt(8)
	s_waitcnt lgkmcnt(0)
	s_barrier
	s_setprio 1
	v_mfma_f32_16x16x32_bf16 v[126:129], v[130:133], v[208:211], v[126:129]
	v_mfma_f32_16x16x32_bf16 v[122:125], v[176:179], v[208:211], v[122:125]
	v_mfma_f32_16x16x32_bf16 v[110:113], v[130:133], v[226:229], v[110:113]
	v_mfma_f32_16x16x32_bf16 v[106:109], v[176:179], v[226:229], v[106:109]
	v_mfma_f32_16x16x32_bf16 v[94:97], v[130:133], v[234:237], v[94:97]
	v_mfma_f32_16x16x32_bf16 v[90:93], v[176:179], v[234:237], v[90:93]
	v_mfma_f32_16x16x32_bf16 v[78:81], v[130:133], v[242:245], v[78:81]
	v_mfma_f32_16x16x32_bf16 v[74:77], v[176:179], v[242:245], v[74:77]
	v_mfma_f32_16x16x32_bf16 v[126:129], v[134:137], v[212:215], v[126:129]
	v_mfma_f32_16x16x32_bf16 v[122:125], v[180:183], v[212:215], v[122:125]
	v_mfma_f32_16x16x32_bf16 v[110:113], v[134:137], v[230:233], v[110:113]
	v_mfma_f32_16x16x32_bf16 v[106:109], v[180:183], v[230:233], v[106:109]
	v_mfma_f32_16x16x32_bf16 v[94:97], v[134:137], v[238:241], v[94:97]
	v_mfma_f32_16x16x32_bf16 v[90:93], v[180:183], v[238:241], v[90:93]
	v_mfma_f32_16x16x32_bf16 v[78:81], v[134:137], v[246:249], v[78:81]
	v_mfma_f32_16x16x32_bf16 v[74:77], v[180:183], v[246:249], v[74:77]
	s_setprio 0
	s_setprio 1
	v_mfma_f32_16x16x32_bf16 v[118:121], v[192:195], v[208:211], v[118:121]
	v_mfma_f32_16x16x32_bf16 v[114:117], v[200:203], v[208:211], v[114:117]
	v_mfma_f32_16x16x32_bf16 v[102:105], v[192:195], v[226:229], v[102:105]
	v_mfma_f32_16x16x32_bf16 v[98:101], v[200:203], v[226:229], v[98:101]
	v_mfma_f32_16x16x32_bf16 v[86:89], v[192:195], v[234:237], v[86:89]
	v_mfma_f32_16x16x32_bf16 v[82:85], v[200:203], v[234:237], v[82:85]
	v_mfma_f32_16x16x32_bf16 v[70:73], v[192:195], v[242:245], v[70:73]
	v_mfma_f32_16x16x32_bf16 v[66:69], v[200:203], v[242:245], v[66:69]
	v_mfma_f32_16x16x32_bf16 v[118:121], v[196:199], v[212:215], v[118:121]
	v_mfma_f32_16x16x32_bf16 v[114:117], v[204:207], v[212:215], v[114:117]
	v_mfma_f32_16x16x32_bf16 v[102:105], v[196:199], v[230:233], v[102:105]
	v_mfma_f32_16x16x32_bf16 v[98:101], v[204:207], v[230:233], v[98:101]
	v_mfma_f32_16x16x32_bf16 v[86:89], v[196:199], v[238:241], v[86:89]
	v_mfma_f32_16x16x32_bf16 v[82:85], v[204:207], v[238:241], v[82:85]
	v_mfma_f32_16x16x32_bf16 v[70:73], v[196:199], v[246:249], v[70:73]
	v_mfma_f32_16x16x32_bf16 v[66:69], v[204:207], v[246:249], v[66:69]
	s_setprio 0
	s_barrier
	s_add_i32 s14, s78, s59
	v_lshl_add_u64 v[184:185], s[50:51], 0, v[140:141]
	s_mov_b32 m0, s14
	ds_read_b128 v[208:211], v190 offset:16384
	ds_read_b128 v[212:215], v190 offset:17408
	ds_read_b128 v[226:229], v190 offset:18432
	ds_read_b128 v[230:233], v190 offset:19456
	ds_read_b128 v[234:237], v190 offset:20480
	ds_read_b128 v[238:241], v190 offset:21504
	ds_read_b128 v[242:245], v190 offset:22528
	ds_read_b128 v[246:249], v190 offset:23552
	global_load_lds_dwordx4 v[184:185], off
	s_add_i32 m0, s14, 0x2000
	s_add_u32 s14, s50, 0x40000
	v_lshl_add_u64 v[216:217], s[50:51], 0, v[144:145]
	s_addc_u32 s15, s51, 0
	s_add_i32 s78, s79, s59
	global_load_lds_dwordx4 v[216:217], off
	v_lshl_add_u64 v[250:251], s[14:15], 0, v[140:141]
	s_mov_b32 m0, s78
	v_lshl_add_u64 v[218:219], s[52:53], 0, v[142:143]
	global_load_lds_dwordx4 v[250:251], off
	v_lshl_add_u64 v[250:251], s[14:15], 0, v[144:145]
	s_add_i32 m0, s78, 0x2000
	s_nop 0
	global_load_lds_dwordx4 v[250:251], off
	v_lshl_add_u64 v[250:251], s[52:53], 0, v[138:139]
	s_mov_b32 m0, s62
	s_nop 0
	global_load_lds_dwordx4 v[250:251], off
	s_mov_b32 m0, s63
	s_nop 0
	global_load_lds_dwordx4 v[218:219], off
	s_waitcnt vmcnt(8)
	s_waitcnt lgkmcnt(0)
	s_barrier
	s_setprio 1
	v_mfma_f32_16x16x32_bf16 v[62:65], v[130:133], v[208:211], v[62:65]
	v_mfma_f32_16x16x32_bf16 v[58:61], v[176:179], v[208:211], v[58:61]
	v_mfma_f32_16x16x32_bf16 v[46:49], v[130:133], v[226:229], v[46:49]
	v_mfma_f32_16x16x32_bf16 v[42:45], v[176:179], v[226:229], v[42:45]
	v_mfma_f32_16x16x32_bf16 v[30:33], v[130:133], v[234:237], v[30:33]
	v_mfma_f32_16x16x32_bf16 v[26:29], v[176:179], v[234:237], v[26:29]
	v_mfma_f32_16x16x32_bf16 v[14:17], v[130:133], v[242:245], v[14:17]
	v_mfma_f32_16x16x32_bf16 v[10:13], v[176:179], v[242:245], v[10:13]
	v_mfma_f32_16x16x32_bf16 v[62:65], v[134:137], v[212:215], v[62:65]
	v_mfma_f32_16x16x32_bf16 v[58:61], v[180:183], v[212:215], v[58:61]
	v_mfma_f32_16x16x32_bf16 v[46:49], v[134:137], v[230:233], v[46:49]
	v_mfma_f32_16x16x32_bf16 v[42:45], v[180:183], v[230:233], v[42:45]
	v_mfma_f32_16x16x32_bf16 v[30:33], v[134:137], v[238:241], v[30:33]
	v_mfma_f32_16x16x32_bf16 v[26:29], v[180:183], v[238:241], v[26:29]
	v_mfma_f32_16x16x32_bf16 v[14:17], v[134:137], v[246:249], v[14:17]
	v_mfma_f32_16x16x32_bf16 v[10:13], v[180:183], v[246:249], v[10:13]
	s_setprio 0
	s_setprio 1
	v_mfma_f32_16x16x32_bf16 v[54:57], v[192:195], v[208:211], v[54:57]
	v_mfma_f32_16x16x32_bf16 v[50:53], v[200:203], v[208:211], v[50:53]
	v_mfma_f32_16x16x32_bf16 v[38:41], v[192:195], v[226:229], v[38:41]
	v_mfma_f32_16x16x32_bf16 v[34:37], v[200:203], v[226:229], v[34:37]
	v_mfma_f32_16x16x32_bf16 v[22:25], v[192:195], v[234:237], v[22:25]
	v_mfma_f32_16x16x32_bf16 v[18:21], v[200:203], v[234:237], v[18:21]
	v_mfma_f32_16x16x32_bf16 v[6:9], v[192:195], v[242:245], v[6:9]
	v_mfma_f32_16x16x32_bf16 v[2:5], v[200:203], v[242:245], v[2:5]
	v_mfma_f32_16x16x32_bf16 v[54:57], v[196:199], v[212:215], v[54:57]
	v_mfma_f32_16x16x32_bf16 v[50:53], v[204:207], v[212:215], v[50:53]
	v_mfma_f32_16x16x32_bf16 v[38:41], v[196:199], v[230:233], v[38:41]
	v_mfma_f32_16x16x32_bf16 v[34:37], v[204:207], v[230:233], v[34:37]
	v_mfma_f32_16x16x32_bf16 v[22:25], v[196:199], v[238:241], v[22:25]
	v_mfma_f32_16x16x32_bf16 v[18:21], v[204:207], v[238:241], v[18:21]
	v_mfma_f32_16x16x32_bf16 v[6:9], v[196:199], v[246:249], v[6:9]
	v_mfma_f32_16x16x32_bf16 v[2:5], v[204:207], v[246:249], v[2:5]
	s_setprio 0
	s_barrier
	s_add_i32 s78, 0, 0x18000
	v_add_u32_e32 v0, s78, v187
	s_add_i32 s79, 0, 0x1c000
	ds_read_b128 v[130:133], v0
	ds_read_b128 v[134:137], v0 offset:1024
	ds_read_b128 v[176:179], v0 offset:2048
	ds_read_b128 v[180:183], v0 offset:3072
	v_add_u32_e32 v0, s79, v187
	ds_read_b128 v[192:195], v0
	ds_read_b128 v[196:199], v0 offset:1024
	ds_read_b128 v[200:203], v0 offset:2048
	ds_read_b128 v[204:207], v0 offset:3072
	s_add_u32 s14, s52, 0x40000
	s_addc_u32 s15, s53, 0
	s_mov_b32 m0, s64
	v_lshl_add_u64 v[220:221], s[14:15], 0, v[138:139]
	ds_read_b128 v[208:211], v190 offset:32768
	ds_read_b128 v[212:215], v190 offset:33792
	ds_read_b128 v[226:229], v190 offset:34816
	ds_read_b128 v[230:233], v190 offset:35840
	ds_read_b128 v[234:237], v190 offset:36864
	ds_read_b128 v[238:241], v190 offset:37888
	ds_read_b128 v[242:245], v190 offset:38912
	ds_read_b128 v[246:249], v190 offset:39936
	global_load_lds_dwordx4 v[220:221], off
	v_lshl_add_u64 v[220:221], s[14:15], 0, v[142:143]
	s_mov_b32 m0, s65
	s_nop 0
	global_load_lds_dwordx4 v[220:221], off
	s_waitcnt vmcnt(8)
	s_waitcnt lgkmcnt(0)
	s_barrier
	s_setprio 1
	v_mfma_f32_16x16x32_bf16 v[126:129], v[130:133], v[208:211], v[126:129]
	v_mfma_f32_16x16x32_bf16 v[122:125], v[176:179], v[208:211], v[122:125]
	v_mfma_f32_16x16x32_bf16 v[110:113], v[130:133], v[226:229], v[110:113]
	v_mfma_f32_16x16x32_bf16 v[106:109], v[176:179], v[226:229], v[106:109]
	v_mfma_f32_16x16x32_bf16 v[94:97], v[130:133], v[234:237], v[94:97]
	v_mfma_f32_16x16x32_bf16 v[90:93], v[176:179], v[234:237], v[90:93]
	v_mfma_f32_16x16x32_bf16 v[78:81], v[130:133], v[242:245], v[78:81]
	v_mfma_f32_16x16x32_bf16 v[74:77], v[176:179], v[242:245], v[74:77]
	v_mfma_f32_16x16x32_bf16 v[126:129], v[134:137], v[212:215], v[126:129]
	v_mfma_f32_16x16x32_bf16 v[122:125], v[180:183], v[212:215], v[122:125]
	v_mfma_f32_16x16x32_bf16 v[110:113], v[134:137], v[230:233], v[110:113]
	v_mfma_f32_16x16x32_bf16 v[106:109], v[180:183], v[230:233], v[106:109]
	v_mfma_f32_16x16x32_bf16 v[94:97], v[134:137], v[238:241], v[94:97]
	v_mfma_f32_16x16x32_bf16 v[90:93], v[180:183], v[238:241], v[90:93]
	v_mfma_f32_16x16x32_bf16 v[78:81], v[134:137], v[246:249], v[78:81]
	v_mfma_f32_16x16x32_bf16 v[74:77], v[180:183], v[246:249], v[74:77]
	s_setprio 0
	s_setprio 1
	v_mfma_f32_16x16x32_bf16 v[118:121], v[192:195], v[208:211], v[118:121]
	v_mfma_f32_16x16x32_bf16 v[114:117], v[200:203], v[208:211], v[114:117]
	v_mfma_f32_16x16x32_bf16 v[102:105], v[192:195], v[226:229], v[102:105]
	v_mfma_f32_16x16x32_bf16 v[98:101], v[200:203], v[226:229], v[98:101]
	v_mfma_f32_16x16x32_bf16 v[86:89], v[192:195], v[234:237], v[86:89]
	v_mfma_f32_16x16x32_bf16 v[82:85], v[200:203], v[234:237], v[82:85]
	v_mfma_f32_16x16x32_bf16 v[70:73], v[192:195], v[242:245], v[70:73]
	v_mfma_f32_16x16x32_bf16 v[66:69], v[200:203], v[242:245], v[66:69]
	v_mfma_f32_16x16x32_bf16 v[118:121], v[196:199], v[212:215], v[118:121]
	v_mfma_f32_16x16x32_bf16 v[114:117], v[204:207], v[212:215], v[114:117]
	v_mfma_f32_16x16x32_bf16 v[102:105], v[196:199], v[230:233], v[102:105]
	v_mfma_f32_16x16x32_bf16 v[98:101], v[204:207], v[230:233], v[98:101]
	v_mfma_f32_16x16x32_bf16 v[86:89], v[196:199], v[238:241], v[86:89]
	v_mfma_f32_16x16x32_bf16 v[82:85], v[204:207], v[238:241], v[82:85]
	v_mfma_f32_16x16x32_bf16 v[70:73], v[196:199], v[246:249], v[70:73]
	v_mfma_f32_16x16x32_bf16 v[66:69], v[204:207], v[246:249], v[66:69]
	s_setprio 0
	s_barrier
	s_add_i32 s14, s78, s59
	v_lshl_add_u64 v[184:185], v[184:185], 0, s[82:83]
	s_mov_b32 m0, s14
	ds_read_b128 v[208:211], v190 offset:49152
	ds_read_b128 v[212:215], v190 offset:50176
	ds_read_b128 v[226:229], v190 offset:51200
	ds_read_b128 v[230:233], v190 offset:52224
	ds_read_b128 v[234:237], v190 offset:53248
	ds_read_b128 v[238:241], v190 offset:54272
	ds_read_b128 v[242:245], v190 offset:55296
	ds_read_b128 v[246:249], v190 offset:56320
	global_load_lds_dwordx4 v[184:185], off
	s_add_i32 m0, s14, 0x2000
	s_add_u32 s14, s50, 0x40080
	v_lshl_add_u64 v[184:185], v[216:217], 0, s[82:83]
	s_addc_u32 s15, s51, 0
	s_add_i32 s50, s79, s59
	global_load_lds_dwordx4 v[184:185], off
	v_lshl_add_u64 v[184:185], s[14:15], 0, v[140:141]
	s_mov_b32 m0, s50
	s_nop 0
	global_load_lds_dwordx4 v[184:185], off
	v_lshl_add_u64 v[184:185], s[14:15], 0, v[144:145]
	s_add_i32 m0, s50, 0x2000
	s_nop 0
	global_load_lds_dwordx4 v[184:185], off
	v_lshl_add_u64 v[184:185], v[250:251], 0, s[82:83]
	s_mov_b32 m0, s67
	s_nop 0
	global_load_lds_dwordx4 v[184:185], off
	v_lshl_add_u64 v[184:185], v[218:219], 0, s[82:83]
	s_mov_b32 m0, s68
	s_nop 0
	global_load_lds_dwordx4 v[184:185], off
	s_waitcnt vmcnt(8)
	s_waitcnt lgkmcnt(0)
	s_barrier
	s_setprio 1
	v_mfma_f32_16x16x32_bf16 v[62:65], v[130:133], v[208:211], v[62:65]
	v_mfma_f32_16x16x32_bf16 v[58:61], v[176:179], v[208:211], v[58:61]
	v_mfma_f32_16x16x32_bf16 v[46:49], v[130:133], v[226:229], v[46:49]
	v_mfma_f32_16x16x32_bf16 v[42:45], v[176:179], v[226:229], v[42:45]
	v_mfma_f32_16x16x32_bf16 v[30:33], v[130:133], v[234:237], v[30:33]
	v_mfma_f32_16x16x32_bf16 v[26:29], v[176:179], v[234:237], v[26:29]
	v_mfma_f32_16x16x32_bf16 v[14:17], v[130:133], v[242:245], v[14:17]
	v_mfma_f32_16x16x32_bf16 v[10:13], v[176:179], v[242:245], v[10:13]
	v_mfma_f32_16x16x32_bf16 v[62:65], v[134:137], v[212:215], v[62:65]
	v_mfma_f32_16x16x32_bf16 v[58:61], v[180:183], v[212:215], v[58:61]
	v_mfma_f32_16x16x32_bf16 v[46:49], v[134:137], v[230:233], v[46:49]
	v_mfma_f32_16x16x32_bf16 v[42:45], v[180:183], v[230:233], v[42:45]
	v_mfma_f32_16x16x32_bf16 v[30:33], v[134:137], v[238:241], v[30:33]
	v_mfma_f32_16x16x32_bf16 v[26:29], v[180:183], v[238:241], v[26:29]
	v_mfma_f32_16x16x32_bf16 v[14:17], v[134:137], v[246:249], v[14:17]
	v_mfma_f32_16x16x32_bf16 v[10:13], v[180:183], v[246:249], v[10:13]
	s_setprio 0
	s_setprio 1
	v_mfma_f32_16x16x32_bf16 v[54:57], v[192:195], v[208:211], v[54:57]
	v_mfma_f32_16x16x32_bf16 v[50:53], v[200:203], v[208:211], v[50:53]
	v_mfma_f32_16x16x32_bf16 v[38:41], v[192:195], v[226:229], v[38:41]
	v_mfma_f32_16x16x32_bf16 v[34:37], v[200:203], v[226:229], v[34:37]
	v_mfma_f32_16x16x32_bf16 v[22:25], v[192:195], v[234:237], v[22:25]
	v_mfma_f32_16x16x32_bf16 v[18:21], v[200:203], v[234:237], v[18:21]
	v_mfma_f32_16x16x32_bf16 v[6:9], v[192:195], v[242:245], v[6:9]
	v_mfma_f32_16x16x32_bf16 v[2:5], v[200:203], v[242:245], v[2:5]
	v_mfma_f32_16x16x32_bf16 v[54:57], v[196:199], v[212:215], v[54:57]
	v_mfma_f32_16x16x32_bf16 v[50:53], v[204:207], v[212:215], v[50:53]
	v_mfma_f32_16x16x32_bf16 v[38:41], v[196:199], v[230:233], v[38:41]
	v_mfma_f32_16x16x32_bf16 v[34:37], v[204:207], v[230:233], v[34:37]
	v_mfma_f32_16x16x32_bf16 v[22:25], v[196:199], v[238:241], v[22:25]
	v_mfma_f32_16x16x32_bf16 v[18:21], v[204:207], v[238:241], v[18:21]
	v_mfma_f32_16x16x32_bf16 v[6:9], v[196:199], v[246:249], v[6:9]
	v_mfma_f32_16x16x32_bf16 v[2:5], v[204:207], v[246:249], v[2:5]
	s_setprio 0
	s_barrier
	s_add_i32 s77, s77, 2
	s_add_u32 s75, s75, 0x100
	s_addc_u32 s76, s76, 0
	s_cmp_gt_u32 s77, 13
	s_cbranch_scc1 .LBB0_331
	s_mov_b64 s[14:15], s[48:49]
	s_branch .LBB0_325

.LBB0_443:
	s_add_u32 s22, s4, 0x100
	s_addc_u32 s23, s5, 0
	s_and_b64 s[24:25], s[24:25], exec
	s_cselect_b32 s27, s49, s23
	s_cselect_b32 s26, s50, s22
	s_cselect_b32 s25, s15, s54
	s_cselect_b32 s24, s51, s53
	s_add_i32 s56, 0, 0x10000
	v_add_u32_e32 v0, s56, v173
	s_add_i32 s57, 0, 0x14000
	ds_read_b128 v[178:181], v0
	ds_read_b128 v[182:185], v0 offset:1024
	ds_read_b128 v[186:189], v0 offset:2048
	ds_read_b128 v[190:193], v0 offset:3072
	v_add_u32_e32 v0, s57, v173
	ds_read_b128 v[194:197], v0
	ds_read_b128 v[198:201], v0 offset:1024
	ds_read_b128 v[202:205], v0 offset:2048
	ds_read_b128 v[206:209], v0 offset:3072
	v_lshl_add_u64 v[218:219], s[4:5], 0, v[138:139]
	s_add_i32 m0, s36, 0xc000
	ds_read_b128 v[210:213], v177
	ds_read_b128 v[214:217], v177 offset:1024
	ds_read_b128 v[226:229], v177 offset:2048
	ds_read_b128 v[230:233], v177 offset:3072
	ds_read_b128 v[234:237], v177 offset:4096
	ds_read_b128 v[238:241], v177 offset:5120
	ds_read_b128 v[242:245], v177 offset:6144
	ds_read_b128 v[246:249], v177 offset:7168
	global_load_lds_dwordx4 v[218:219], off
	v_lshl_add_u64 v[218:219], s[4:5], 0, v[140:141]
	s_add_i32 m0, s36, 0xe000
	s_nop 0
	global_load_lds_dwordx4 v[218:219], off
	s_waitcnt vmcnt(8)
	s_waitcnt lgkmcnt(0)
	s_barrier
	s_setprio 1
	v_mfma_f32_16x16x32_bf16 v[126:129], v[178:181], v[210:213], v[126:129]
	v_mfma_f32_16x16x32_bf16 v[122:125], v[186:189], v[210:213], v[122:125]
	v_mfma_f32_16x16x32_bf16 v[110:113], v[178:181], v[226:229], v[110:113]
	v_mfma_f32_16x16x32_bf16 v[106:109], v[186:189], v[226:229], v[106:109]
	v_mfma_f32_16x16x32_bf16 v[94:97], v[178:181], v[234:237], v[94:97]
	v_mfma_f32_16x16x32_bf16 v[90:93], v[186:189], v[234:237], v[90:93]
	v_mfma_f32_16x16x32_bf16 v[78:81], v[178:181], v[242:245], v[78:81]
	v_mfma_f32_16x16x32_bf16 v[74:77], v[186:189], v[242:245], v[74:77]
	v_mfma_f32_16x16x32_bf16 v[126:129], v[182:185], v[214:217], v[126:129]
	v_mfma_f32_16x16x32_bf16 v[122:125], v[190:193], v[214:217], v[122:125]
	v_mfma_f32_16x16x32_bf16 v[110:113], v[182:185], v[230:233], v[110:113]
	v_mfma_f32_16x16x32_bf16 v[106:109], v[190:193], v[230:233], v[106:109]
	v_mfma_f32_16x16x32_bf16 v[94:97], v[182:185], v[238:241], v[94:97]
	v_mfma_f32_16x16x32_bf16 v[90:93], v[190:193], v[238:241], v[90:93]
	v_mfma_f32_16x16x32_bf16 v[78:81], v[182:185], v[246:249], v[78:81]
	v_mfma_f32_16x16x32_bf16 v[74:77], v[190:193], v[246:249], v[74:77]
	s_setprio 0
	s_setprio 1
	v_mfma_f32_16x16x32_bf16 v[118:121], v[194:197], v[210:213], v[118:121]
	v_mfma_f32_16x16x32_bf16 v[114:117], v[202:205], v[210:213], v[114:117]
	v_mfma_f32_16x16x32_bf16 v[102:105], v[194:197], v[226:229], v[102:105]
	v_mfma_f32_16x16x32_bf16 v[98:101], v[202:205], v[226:229], v[98:101]
	v_mfma_f32_16x16x32_bf16 v[86:89], v[194:197], v[234:237], v[86:89]
	v_mfma_f32_16x16x32_bf16 v[82:85], v[202:205], v[234:237], v[82:85]
	v_mfma_f32_16x16x32_bf16 v[70:73], v[194:197], v[242:245], v[70:73]
	v_mfma_f32_16x16x32_bf16 v[66:69], v[202:205], v[242:245], v[66:69]
	v_mfma_f32_16x16x32_bf16 v[118:121], v[198:201], v[214:217], v[118:121]
	v_mfma_f32_16x16x32_bf16 v[114:117], v[206:209], v[214:217], v[114:117]
	v_mfma_f32_16x16x32_bf16 v[102:105], v[198:201], v[230:233], v[102:105]
	v_mfma_f32_16x16x32_bf16 v[98:101], v[206:209], v[230:233], v[98:101]
	v_mfma_f32_16x16x32_bf16 v[86:89], v[198:201], v[238:241], v[86:89]
	v_mfma_f32_16x16x32_bf16 v[82:85], v[206:209], v[238:241], v[82:85]
	v_mfma_f32_16x16x32_bf16 v[70:73], v[198:201], v[246:249], v[70:73]
	v_mfma_f32_16x16x32_bf16 v[66:69], v[206:209], v[246:249], v[66:69]
	s_setprio 0
	s_barrier
	s_add_i32 s4, s56, s35
	v_lshl_add_u64 v[218:219], s[24:25], 0, v[132:133]
	s_mov_b32 m0, s4
	ds_read_b128 v[210:213], v177 offset:16384
	ds_read_b128 v[214:217], v177 offset:17408
	ds_read_b128 v[226:229], v177 offset:18432
	ds_read_b128 v[230:233], v177 offset:19456
	ds_read_b128 v[234:237], v177 offset:20480
	ds_read_b128 v[238:241], v177 offset:21504
	ds_read_b128 v[242:245], v177 offset:22528
	ds_read_b128 v[246:249], v177 offset:23552
	global_load_lds_dwordx4 v[218:219], off
	s_add_i32 m0, s4, 0x2000
	s_add_u32 s4, s24, 0x40000
	v_lshl_add_u64 v[220:221], s[24:25], 0, v[136:137]
	s_addc_u32 s5, s25, 0
	s_add_i32 s56, s57, s35
	global_load_lds_dwordx4 v[220:221], off
	v_lshl_add_u64 v[250:251], s[4:5], 0, v[132:133]
	s_mov_b32 m0, s56
	v_lshl_add_u64 v[162:163], s[26:27], 0, v[134:135]
	global_load_lds_dwordx4 v[250:251], off
	v_lshl_add_u64 v[250:251], s[4:5], 0, v[136:137]
	s_add_i32 m0, s56, 0x2000
	s_nop 0
	global_load_lds_dwordx4 v[250:251], off
	v_lshl_add_u64 v[250:251], s[26:27], 0, v[130:131]
	s_mov_b32 m0, s36
	s_nop 0
	global_load_lds_dwordx4 v[250:251], off
	s_mov_b32 m0, s37
	s_nop 0
	global_load_lds_dwordx4 v[162:163], off
	s_waitcnt vmcnt(8)
	s_waitcnt lgkmcnt(0)
	s_barrier
	s_setprio 1
	v_mfma_f32_16x16x32_bf16 v[62:65], v[178:181], v[210:213], v[62:65]
	v_mfma_f32_16x16x32_bf16 v[58:61], v[186:189], v[210:213], v[58:61]
	v_mfma_f32_16x16x32_bf16 v[50:53], v[178:181], v[226:229], v[50:53]
	v_mfma_f32_16x16x32_bf16 v[42:45], v[186:189], v[226:229], v[42:45]
	v_mfma_f32_16x16x32_bf16 v[34:37], v[178:181], v[234:237], v[34:37]
	v_mfma_f32_16x16x32_bf16 v[26:29], v[186:189], v[234:237], v[26:29]
	v_mfma_f32_16x16x32_bf16 v[18:21], v[178:181], v[242:245], v[18:21]
	v_mfma_f32_16x16x32_bf16 v[10:13], v[186:189], v[242:245], v[10:13]
	v_mfma_f32_16x16x32_bf16 v[62:65], v[182:185], v[214:217], v[62:65]
	v_mfma_f32_16x16x32_bf16 v[58:61], v[190:193], v[214:217], v[58:61]
	v_mfma_f32_16x16x32_bf16 v[50:53], v[182:185], v[230:233], v[50:53]
	v_mfma_f32_16x16x32_bf16 v[42:45], v[190:193], v[230:233], v[42:45]
	v_mfma_f32_16x16x32_bf16 v[34:37], v[182:185], v[238:241], v[34:37]
	v_mfma_f32_16x16x32_bf16 v[26:29], v[190:193], v[238:241], v[26:29]
	v_mfma_f32_16x16x32_bf16 v[18:21], v[182:185], v[246:249], v[18:21]
	v_mfma_f32_16x16x32_bf16 v[10:13], v[190:193], v[246:249], v[10:13]
	s_setprio 0
	s_setprio 1
	v_mfma_f32_16x16x32_bf16 v[54:57], v[194:197], v[210:213], v[54:57]
	v_mfma_f32_16x16x32_bf16 v[46:49], v[202:205], v[210:213], v[46:49]
	v_mfma_f32_16x16x32_bf16 v[38:41], v[194:197], v[226:229], v[38:41]
	v_mfma_f32_16x16x32_bf16 v[30:33], v[202:205], v[226:229], v[30:33]
	v_mfma_f32_16x16x32_bf16 v[22:25], v[194:197], v[234:237], v[22:25]
	v_mfma_f32_16x16x32_bf16 v[14:17], v[202:205], v[234:237], v[14:17]
	v_mfma_f32_16x16x32_bf16 v[6:9], v[194:197], v[242:245], v[6:9]
	v_mfma_f32_16x16x32_bf16 v[2:5], v[202:205], v[242:245], v[2:5]
	v_mfma_f32_16x16x32_bf16 v[54:57], v[198:201], v[214:217], v[54:57]
	v_mfma_f32_16x16x32_bf16 v[46:49], v[206:209], v[214:217], v[46:49]
	v_mfma_f32_16x16x32_bf16 v[38:41], v[198:201], v[230:233], v[38:41]
	v_mfma_f32_16x16x32_bf16 v[30:33], v[206:209], v[230:233], v[30:33]
	v_mfma_f32_16x16x32_bf16 v[22:25], v[198:201], v[238:241], v[22:25]
	v_mfma_f32_16x16x32_bf16 v[14:17], v[206:209], v[238:241], v[14:17]
	v_mfma_f32_16x16x32_bf16 v[6:9], v[198:201], v[246:249], v[6:9]
	v_mfma_f32_16x16x32_bf16 v[2:5], v[206:209], v[246:249], v[2:5]
	s_setprio 0
	s_barrier
	s_add_i32 s56, 0, 0x18000
	v_add_u32_e32 v0, s56, v173
	s_add_i32 s57, 0, 0x1c000
	ds_read_b128 v[178:181], v0
	ds_read_b128 v[182:185], v0 offset:1024
	ds_read_b128 v[186:189], v0 offset:2048
	ds_read_b128 v[190:193], v0 offset:3072
	v_add_u32_e32 v0, s57, v173
	ds_read_b128 v[194:197], v0
	ds_read_b128 v[198:201], v0 offset:1024
	ds_read_b128 v[202:205], v0 offset:2048
	ds_read_b128 v[206:209], v0 offset:3072
	s_add_u32 s4, s26, 0x40000
	s_addc_u32 s5, s27, 0
	s_mov_b32 m0, s38
	v_lshl_add_u64 v[158:159], s[4:5], 0, v[130:131]
	ds_read_b128 v[210:213], v177 offset:32768
	ds_read_b128 v[214:217], v177 offset:33792
	ds_read_b128 v[226:229], v177 offset:34816
	ds_read_b128 v[230:233], v177 offset:35840
	ds_read_b128 v[234:237], v177 offset:36864
	ds_read_b128 v[238:241], v177 offset:37888
	ds_read_b128 v[242:245], v177 offset:38912
	ds_read_b128 v[246:249], v177 offset:39936
	global_load_lds_dwordx4 v[158:159], off
	v_lshl_add_u64 v[158:159], s[4:5], 0, v[134:135]
	s_mov_b32 m0, s39
	s_nop 0
	global_load_lds_dwordx4 v[158:159], off
	s_waitcnt vmcnt(8)
	s_waitcnt lgkmcnt(0)
	s_barrier
	s_setprio 1
	v_mfma_f32_16x16x32_bf16 v[126:129], v[178:181], v[210:213], v[126:129]
	v_mfma_f32_16x16x32_bf16 v[122:125], v[186:189], v[210:213], v[122:125]
	v_mfma_f32_16x16x32_bf16 v[110:113], v[178:181], v[226:229], v[110:113]
	v_mfma_f32_16x16x32_bf16 v[106:109], v[186:189], v[226:229], v[106:109]
	v_mfma_f32_16x16x32_bf16 v[94:97], v[178:181], v[234:237], v[94:97]
	v_mfma_f32_16x16x32_bf16 v[90:93], v[186:189], v[234:237], v[90:93]
	v_mfma_f32_16x16x32_bf16 v[78:81], v[178:181], v[242:245], v[78:81]
	v_mfma_f32_16x16x32_bf16 v[74:77], v[186:189], v[242:245], v[74:77]
	v_mfma_f32_16x16x32_bf16 v[126:129], v[182:185], v[214:217], v[126:129]
	v_mfma_f32_16x16x32_bf16 v[122:125], v[190:193], v[214:217], v[122:125]
	v_mfma_f32_16x16x32_bf16 v[110:113], v[182:185], v[230:233], v[110:113]
	v_mfma_f32_16x16x32_bf16 v[106:109], v[190:193], v[230:233], v[106:109]
	v_mfma_f32_16x16x32_bf16 v[94:97], v[182:185], v[238:241], v[94:97]
	v_mfma_f32_16x16x32_bf16 v[90:93], v[190:193], v[238:241], v[90:93]
	v_mfma_f32_16x16x32_bf16 v[78:81], v[182:185], v[246:249], v[78:81]
	v_mfma_f32_16x16x32_bf16 v[74:77], v[190:193], v[246:249], v[74:77]
	s_setprio 0
	s_setprio 1
	v_mfma_f32_16x16x32_bf16 v[118:121], v[194:197], v[210:213], v[118:121]
	v_mfma_f32_16x16x32_bf16 v[114:117], v[202:205], v[210:213], v[114:117]
	v_mfma_f32_16x16x32_bf16 v[102:105], v[194:197], v[226:229], v[102:105]
	v_mfma_f32_16x16x32_bf16 v[98:101], v[202:205], v[226:229], v[98:101]
	v_mfma_f32_16x16x32_bf16 v[86:89], v[194:197], v[234:237], v[86:89]
	v_mfma_f32_16x16x32_bf16 v[82:85], v[202:205], v[234:237], v[82:85]
	v_mfma_f32_16x16x32_bf16 v[70:73], v[194:197], v[242:245], v[70:73]
	v_mfma_f32_16x16x32_bf16 v[66:69], v[202:205], v[242:245], v[66:69]
	v_mfma_f32_16x16x32_bf16 v[118:121], v[198:201], v[214:217], v[118:121]
	v_mfma_f32_16x16x32_bf16 v[114:117], v[206:209], v[214:217], v[114:117]
	v_mfma_f32_16x16x32_bf16 v[102:105], v[198:201], v[230:233], v[102:105]
	v_mfma_f32_16x16x32_bf16 v[98:101], v[206:209], v[230:233], v[98:101]
	v_mfma_f32_16x16x32_bf16 v[86:89], v[198:201], v[238:241], v[86:89]
	v_mfma_f32_16x16x32_bf16 v[82:85], v[206:209], v[238:241], v[82:85]
	v_mfma_f32_16x16x32_bf16 v[70:73], v[198:201], v[246:249], v[70:73]
	v_mfma_f32_16x16x32_bf16 v[66:69], v[206:209], v[246:249], v[66:69]
	s_setprio 0
	s_barrier
	s_add_i32 s4, s56, s35
	v_lshl_add_u64 v[158:159], v[218:219], 0, s[82:83]
	s_mov_b32 m0, s4
	ds_read_b128 v[210:213], v177 offset:49152
	ds_read_b128 v[214:217], v177 offset:50176
	ds_read_b128 v[226:229], v177 offset:51200
	ds_read_b128 v[230:233], v177 offset:52224
	ds_read_b128 v[234:237], v177 offset:53248
	ds_read_b128 v[238:241], v177 offset:54272
	ds_read_b128 v[242:245], v177 offset:55296
	ds_read_b128 v[246:249], v177 offset:56320
	global_load_lds_dwordx4 v[158:159], off
	s_add_i32 m0, s4, 0x2000
	s_add_u32 s4, s24, 0x40080
	v_lshl_add_u64 v[158:159], v[220:221], 0, s[82:83]
	s_addc_u32 s5, s25, 0
	s_add_i32 s24, s57, s35
	global_load_lds_dwordx4 v[158:159], off
	v_lshl_add_u64 v[158:159], s[4:5], 0, v[132:133]
	s_mov_b32 m0, s24
	s_nop 0
	global_load_lds_dwordx4 v[158:159], off
	v_lshl_add_u64 v[158:159], s[4:5], 0, v[136:137]
	s_add_i32 m0, s24, 0x2000
	s_nop 0
	global_load_lds_dwordx4 v[158:159], off
	v_lshl_add_u64 v[158:159], v[250:251], 0, s[82:83]
	s_mov_b32 m0, s41
	s_nop 0
	global_load_lds_dwordx4 v[158:159], off
	v_lshl_add_u64 v[158:159], v[162:163], 0, s[82:83]
	s_mov_b32 m0, s42
	s_nop 0
	global_load_lds_dwordx4 v[158:159], off
	s_waitcnt vmcnt(8)
	s_waitcnt lgkmcnt(0)
	s_barrier
	s_setprio 1
	v_mfma_f32_16x16x32_bf16 v[62:65], v[178:181], v[210:213], v[62:65]
	v_mfma_f32_16x16x32_bf16 v[58:61], v[186:189], v[210:213], v[58:61]
	v_mfma_f32_16x16x32_bf16 v[50:53], v[178:181], v[226:229], v[50:53]
	v_mfma_f32_16x16x32_bf16 v[42:45], v[186:189], v[226:229], v[42:45]
	v_mfma_f32_16x16x32_bf16 v[34:37], v[178:181], v[234:237], v[34:37]
	v_mfma_f32_16x16x32_bf16 v[26:29], v[186:189], v[234:237], v[26:29]
	v_mfma_f32_16x16x32_bf16 v[18:21], v[178:181], v[242:245], v[18:21]
	v_mfma_f32_16x16x32_bf16 v[10:13], v[186:189], v[242:245], v[10:13]
	v_mfma_f32_16x16x32_bf16 v[62:65], v[182:185], v[214:217], v[62:65]
	v_mfma_f32_16x16x32_bf16 v[58:61], v[190:193], v[214:217], v[58:61]
	v_mfma_f32_16x16x32_bf16 v[50:53], v[182:185], v[230:233], v[50:53]
	v_mfma_f32_16x16x32_bf16 v[42:45], v[190:193], v[230:233], v[42:45]
	v_mfma_f32_16x16x32_bf16 v[34:37], v[182:185], v[238:241], v[34:37]
	v_mfma_f32_16x16x32_bf16 v[26:29], v[190:193], v[238:241], v[26:29]
	v_mfma_f32_16x16x32_bf16 v[18:21], v[182:185], v[246:249], v[18:21]
	v_mfma_f32_16x16x32_bf16 v[10:13], v[190:193], v[246:249], v[10:13]
	s_setprio 0
	s_setprio 1
	v_mfma_f32_16x16x32_bf16 v[54:57], v[194:197], v[210:213], v[54:57]
	v_mfma_f32_16x16x32_bf16 v[46:49], v[202:205], v[210:213], v[46:49]
	v_mfma_f32_16x16x32_bf16 v[38:41], v[194:197], v[226:229], v[38:41]
	v_mfma_f32_16x16x32_bf16 v[30:33], v[202:205], v[226:229], v[30:33]
	v_mfma_f32_16x16x32_bf16 v[22:25], v[194:197], v[234:237], v[22:25]
	v_mfma_f32_16x16x32_bf16 v[14:17], v[202:205], v[234:237], v[14:17]
	v_mfma_f32_16x16x32_bf16 v[6:9], v[194:197], v[242:245], v[6:9]
	v_mfma_f32_16x16x32_bf16 v[2:5], v[202:205], v[242:245], v[2:5]
	v_mfma_f32_16x16x32_bf16 v[54:57], v[198:201], v[214:217], v[54:57]
	v_mfma_f32_16x16x32_bf16 v[46:49], v[206:209], v[214:217], v[46:49]
	v_mfma_f32_16x16x32_bf16 v[38:41], v[198:201], v[230:233], v[38:41]
	v_mfma_f32_16x16x32_bf16 v[30:33], v[206:209], v[230:233], v[30:33]
	v_mfma_f32_16x16x32_bf16 v[22:25], v[198:201], v[238:241], v[22:25]
	v_mfma_f32_16x16x32_bf16 v[14:17], v[206:209], v[238:241], v[14:17]
	v_mfma_f32_16x16x32_bf16 v[6:9], v[198:201], v[246:249], v[6:9]
	v_mfma_f32_16x16x32_bf16 v[2:5], v[206:209], v[246:249], v[2:5]
	s_setprio 0
	s_barrier
	s_add_i32 s55, s55, 2
	s_add_u32 s53, s53, 0x100
	s_addc_u32 s54, s54, 0
	s_cmp_gt_u32 s55, 13
	s_cbranch_scc1 .LBB0_445
	s_mov_b64 s[4:5], s[22:23]
	s_branch .LBB0_439

.LBB0_693:
	s_add_u32 s24, s22, 0xfffc0080
	s_addc_u32 s25, s23, -1
	s_add_i32 s48, 0, 0x10000
	s_cmp_eq_u32 s47, 12
	s_cselect_b32 s27, s17, s25
	s_cselect_b32 s26, s43, s24
	s_cselect_b32 s25, s15, s46
	s_cselect_b32 s24, s44, s45
	s_add_i32 s50, 0, 0x14000
	v_add_u32_e32 v134, s48, v191
	v_add_u32_e32 v158, s50, v191
	ds_read_b128 v[114:117], v134
	ds_read_b128 v[118:121], v134 offset:1024
	ds_read_b128 v[122:125], v134 offset:2048
	ds_read_b128 v[134:137], v134 offset:3072
	ds_read_b128 v[146:149], v158
	ds_read_b128 v[150:153], v158 offset:1024
	ds_read_b128 v[172:175], v158 offset:2048
	ds_read_b128 v[176:179], v158 offset:3072
	v_lshl_add_u64 v[158:159], s[22:23], 0, v[168:169]
	s_add_i32 m0, s34, 0xc000
	ds_read_b128 v[180:183], v193
	ds_read_b128 v[184:187], v193 offset:1024
	ds_read_b128 v[194:197], v193 offset:2048
	ds_read_b128 v[198:201], v193 offset:3072
	ds_read_b128 v[202:205], v193 offset:4096
	ds_read_b128 v[206:209], v193 offset:5120
	ds_read_b128 v[210:213], v193 offset:6144
	ds_read_b128 v[214:217], v193 offset:7168
	global_load_lds_dwordx4 v[158:159], off
	v_lshl_add_u64 v[158:159], s[22:23], 0, v[170:171]
	s_add_i32 m0, s34, 0xe000
	s_nop 0
	global_load_lds_dwordx4 v[158:159], off
	s_waitcnt vmcnt(8)
	s_waitcnt lgkmcnt(0)
	s_barrier
	s_setprio 1
	v_mfma_f32_16x16x32_bf16 v[142:145], v[114:117], v[180:183], v[142:145]
	v_mfma_f32_16x16x32_bf16 v[138:141], v[122:125], v[180:183], v[138:141]
	v_mfma_f32_16x16x32_bf16 v[110:113], v[114:117], v[194:197], v[110:113]
	v_mfma_f32_16x16x32_bf16 v[106:109], v[122:125], v[194:197], v[106:109]
	v_mfma_f32_16x16x32_bf16 v[94:97], v[114:117], v[202:205], v[94:97]
	v_mfma_f32_16x16x32_bf16 v[90:93], v[122:125], v[202:205], v[90:93]
	v_mfma_f32_16x16x32_bf16 v[78:81], v[114:117], v[210:213], v[78:81]
	v_mfma_f32_16x16x32_bf16 v[74:77], v[122:125], v[210:213], v[74:77]
	v_mfma_f32_16x16x32_bf16 v[142:145], v[118:121], v[184:187], v[142:145]
	v_mfma_f32_16x16x32_bf16 v[138:141], v[134:137], v[184:187], v[138:141]
	v_mfma_f32_16x16x32_bf16 v[110:113], v[118:121], v[198:201], v[110:113]
	v_mfma_f32_16x16x32_bf16 v[106:109], v[134:137], v[198:201], v[106:109]
	v_mfma_f32_16x16x32_bf16 v[94:97], v[118:121], v[206:209], v[94:97]
	v_mfma_f32_16x16x32_bf16 v[90:93], v[134:137], v[206:209], v[90:93]
	v_mfma_f32_16x16x32_bf16 v[78:81], v[118:121], v[214:217], v[78:81]
	v_mfma_f32_16x16x32_bf16 v[74:77], v[134:137], v[214:217], v[74:77]
	s_setprio 0
	s_setprio 1
	v_mfma_f32_16x16x32_bf16 v[130:133], v[146:149], v[180:183], v[130:133]
	v_mfma_f32_16x16x32_bf16 v[126:129], v[172:175], v[180:183], v[126:129]
	v_mfma_f32_16x16x32_bf16 v[102:105], v[146:149], v[194:197], v[102:105]
	v_mfma_f32_16x16x32_bf16 v[98:101], v[172:175], v[194:197], v[98:101]
	v_mfma_f32_16x16x32_bf16 v[86:89], v[146:149], v[202:205], v[86:89]
	v_mfma_f32_16x16x32_bf16 v[82:85], v[172:175], v[202:205], v[82:85]
	v_mfma_f32_16x16x32_bf16 v[70:73], v[146:149], v[210:213], v[70:73]
	v_mfma_f32_16x16x32_bf16 v[66:69], v[172:175], v[210:213], v[66:69]
	v_mfma_f32_16x16x32_bf16 v[130:133], v[150:153], v[184:187], v[130:133]
	v_mfma_f32_16x16x32_bf16 v[126:129], v[176:179], v[184:187], v[126:129]
	v_mfma_f32_16x16x32_bf16 v[102:105], v[150:153], v[198:201], v[102:105]
	v_mfma_f32_16x16x32_bf16 v[98:101], v[176:179], v[198:201], v[98:101]
	v_mfma_f32_16x16x32_bf16 v[86:89], v[150:153], v[206:209], v[86:89]
	v_mfma_f32_16x16x32_bf16 v[82:85], v[176:179], v[206:209], v[82:85]
	v_mfma_f32_16x16x32_bf16 v[70:73], v[150:153], v[214:217], v[70:73]
	v_mfma_f32_16x16x32_bf16 v[66:69], v[176:179], v[214:217], v[66:69]
	s_setprio 0
	s_barrier
	s_add_i32 s48, s48, s33
	v_lshl_add_u64 v[158:159], s[24:25], 0, v[0:1]
	s_mov_b32 m0, s48
	ds_read_b128 v[180:183], v193 offset:16384
	ds_read_b128 v[184:187], v193 offset:17408
	ds_read_b128 v[194:197], v193 offset:18432
	ds_read_b128 v[198:201], v193 offset:19456
	ds_read_b128 v[202:205], v193 offset:20480
	ds_read_b128 v[206:209], v193 offset:21504
	ds_read_b128 v[210:213], v193 offset:22528
	ds_read_b128 v[214:217], v193 offset:23552
	global_load_lds_dwordx4 v[158:159], off
	s_add_i32 m0, s48, 0x2000
	s_add_u32 s48, s24, 0x40000
	v_lshl_add_u64 v[162:163], s[24:25], 0, v[154:155]
	s_addc_u32 s49, s25, 0
	s_add_i32 s50, s50, s33
	global_load_lds_dwordx4 v[162:163], off
	v_lshl_add_u64 v[188:189], s[48:49], 0, v[0:1]
	s_mov_b32 m0, s50
	v_lshl_add_u64 v[218:219], s[26:27], 0, v[156:157]
	global_load_lds_dwordx4 v[188:189], off
	v_lshl_add_u64 v[188:189], s[48:49], 0, v[154:155]
	s_add_i32 m0, s50, 0x2000
	s_nop 0
	global_load_lds_dwordx4 v[188:189], off
	v_lshl_add_u64 v[188:189], s[26:27], 0, v[166:167]
	s_mov_b32 m0, s34
	s_nop 0
	global_load_lds_dwordx4 v[188:189], off
	s_mov_b32 m0, s35
	s_nop 0
	global_load_lds_dwordx4 v[218:219], off
	s_waitcnt vmcnt(8)
	s_waitcnt lgkmcnt(0)
	s_barrier
	s_setprio 1
	v_mfma_f32_16x16x32_bf16 v[62:65], v[114:117], v[180:183], v[62:65]
	v_mfma_f32_16x16x32_bf16 v[58:61], v[122:125], v[180:183], v[58:61]
	v_mfma_f32_16x16x32_bf16 v[46:49], v[114:117], v[194:197], v[46:49]
	v_mfma_f32_16x16x32_bf16 v[42:45], v[122:125], v[194:197], v[42:45]
	v_mfma_f32_16x16x32_bf16 v[30:33], v[114:117], v[202:205], v[30:33]
	v_mfma_f32_16x16x32_bf16 v[26:29], v[122:125], v[202:205], v[26:29]
	v_mfma_f32_16x16x32_bf16 v[14:17], v[114:117], v[210:213], v[14:17]
	v_mfma_f32_16x16x32_bf16 v[10:13], v[122:125], v[210:213], v[10:13]
	v_mfma_f32_16x16x32_bf16 v[62:65], v[118:121], v[184:187], v[62:65]
	v_mfma_f32_16x16x32_bf16 v[58:61], v[134:137], v[184:187], v[58:61]
	v_mfma_f32_16x16x32_bf16 v[46:49], v[118:121], v[198:201], v[46:49]
	v_mfma_f32_16x16x32_bf16 v[42:45], v[134:137], v[198:201], v[42:45]
	v_mfma_f32_16x16x32_bf16 v[30:33], v[118:121], v[206:209], v[30:33]
	v_mfma_f32_16x16x32_bf16 v[26:29], v[134:137], v[206:209], v[26:29]
	v_mfma_f32_16x16x32_bf16 v[14:17], v[118:121], v[214:217], v[14:17]
	v_mfma_f32_16x16x32_bf16 v[10:13], v[134:137], v[214:217], v[10:13]
	s_setprio 0
	s_setprio 1
	v_mfma_f32_16x16x32_bf16 v[54:57], v[146:149], v[180:183], v[54:57]
	v_mfma_f32_16x16x32_bf16 v[50:53], v[172:175], v[180:183], v[50:53]
	v_mfma_f32_16x16x32_bf16 v[38:41], v[146:149], v[194:197], v[38:41]
	v_mfma_f32_16x16x32_bf16 v[34:37], v[172:175], v[194:197], v[34:37]
	v_mfma_f32_16x16x32_bf16 v[22:25], v[146:149], v[202:205], v[22:25]
	v_mfma_f32_16x16x32_bf16 v[18:21], v[172:175], v[202:205], v[18:21]
	v_mfma_f32_16x16x32_bf16 v[6:9], v[146:149], v[210:213], v[6:9]
	v_mfma_f32_16x16x32_bf16 v[2:5], v[172:175], v[210:213], v[2:5]
	v_mfma_f32_16x16x32_bf16 v[54:57], v[150:153], v[184:187], v[54:57]
	v_mfma_f32_16x16x32_bf16 v[50:53], v[176:179], v[184:187], v[50:53]
	v_mfma_f32_16x16x32_bf16 v[38:41], v[150:153], v[198:201], v[38:41]
	v_mfma_f32_16x16x32_bf16 v[34:37], v[176:179], v[198:201], v[34:37]
	v_mfma_f32_16x16x32_bf16 v[22:25], v[150:153], v[206:209], v[22:25]
	v_mfma_f32_16x16x32_bf16 v[18:21], v[176:179], v[206:209], v[18:21]
	v_mfma_f32_16x16x32_bf16 v[6:9], v[150:153], v[214:217], v[6:9]
	v_mfma_f32_16x16x32_bf16 v[2:5], v[176:179], v[214:217], v[2:5]
	s_setprio 0
	s_barrier
	s_add_i32 s48, 0, 0x18000
	s_add_i32 s49, 0, 0x1c000
	v_add_u32_e32 v134, s48, v191
	v_add_u32_e32 v176, s49, v191
	ds_read_b128 v[114:117], v134
	ds_read_b128 v[118:121], v134 offset:1024
	ds_read_b128 v[122:125], v134 offset:2048
	ds_read_b128 v[134:137], v134 offset:3072
	ds_read_b128 v[146:149], v176
	ds_read_b128 v[150:153], v176 offset:1024
	ds_read_b128 v[172:175], v176 offset:2048
	ds_read_b128 v[176:179], v176 offset:3072
	s_add_u32 s26, s26, 0x40000
	s_addc_u32 s27, s27, 0
	s_mov_b32 m0, s36
	v_lshl_add_u64 v[220:221], s[26:27], 0, v[166:167]
	ds_read_b128 v[180:183], v193 offset:32768
	ds_read_b128 v[184:187], v193 offset:33792
	ds_read_b128 v[194:197], v193 offset:34816
	ds_read_b128 v[198:201], v193 offset:35840
	ds_read_b128 v[202:205], v193 offset:36864
	ds_read_b128 v[206:209], v193 offset:37888
	ds_read_b128 v[210:213], v193 offset:38912
	ds_read_b128 v[214:217], v193 offset:39936
	global_load_lds_dwordx4 v[220:221], off
	v_lshl_add_u64 v[220:221], s[26:27], 0, v[156:157]
	s_mov_b32 m0, s37
	s_nop 0
	global_load_lds_dwordx4 v[220:221], off
	s_waitcnt vmcnt(8)
	s_waitcnt lgkmcnt(0)
	s_barrier
	s_setprio 1
	v_mfma_f32_16x16x32_bf16 v[142:145], v[114:117], v[180:183], v[142:145]
	v_mfma_f32_16x16x32_bf16 v[138:141], v[122:125], v[180:183], v[138:141]
	v_mfma_f32_16x16x32_bf16 v[110:113], v[114:117], v[194:197], v[110:113]
	v_mfma_f32_16x16x32_bf16 v[106:109], v[122:125], v[194:197], v[106:109]
	v_mfma_f32_16x16x32_bf16 v[94:97], v[114:117], v[202:205], v[94:97]
	v_mfma_f32_16x16x32_bf16 v[90:93], v[122:125], v[202:205], v[90:93]
	v_mfma_f32_16x16x32_bf16 v[78:81], v[114:117], v[210:213], v[78:81]
	v_mfma_f32_16x16x32_bf16 v[74:77], v[122:125], v[210:213], v[74:77]
	v_mfma_f32_16x16x32_bf16 v[142:145], v[118:121], v[184:187], v[142:145]
	v_mfma_f32_16x16x32_bf16 v[138:141], v[134:137], v[184:187], v[138:141]
	v_mfma_f32_16x16x32_bf16 v[110:113], v[118:121], v[198:201], v[110:113]
	v_mfma_f32_16x16x32_bf16 v[106:109], v[134:137], v[198:201], v[106:109]
	v_mfma_f32_16x16x32_bf16 v[94:97], v[118:121], v[206:209], v[94:97]
	v_mfma_f32_16x16x32_bf16 v[90:93], v[134:137], v[206:209], v[90:93]
	v_mfma_f32_16x16x32_bf16 v[78:81], v[118:121], v[214:217], v[78:81]
	v_mfma_f32_16x16x32_bf16 v[74:77], v[134:137], v[214:217], v[74:77]
	s_setprio 0
	s_setprio 1
	v_mfma_f32_16x16x32_bf16 v[130:133], v[146:149], v[180:183], v[130:133]
	v_mfma_f32_16x16x32_bf16 v[126:129], v[172:175], v[180:183], v[126:129]
	v_mfma_f32_16x16x32_bf16 v[102:105], v[146:149], v[194:197], v[102:105]
	v_mfma_f32_16x16x32_bf16 v[98:101], v[172:175], v[194:197], v[98:101]
	v_mfma_f32_16x16x32_bf16 v[86:89], v[146:149], v[202:205], v[86:89]
	v_mfma_f32_16x16x32_bf16 v[82:85], v[172:175], v[202:205], v[82:85]
	v_mfma_f32_16x16x32_bf16 v[70:73], v[146:149], v[210:213], v[70:73]
	v_mfma_f32_16x16x32_bf16 v[66:69], v[172:175], v[210:213], v[66:69]
	v_mfma_f32_16x16x32_bf16 v[130:133], v[150:153], v[184:187], v[130:133]
	v_mfma_f32_16x16x32_bf16 v[126:129], v[176:179], v[184:187], v[126:129]
	v_mfma_f32_16x16x32_bf16 v[102:105], v[150:153], v[198:201], v[102:105]
	v_mfma_f32_16x16x32_bf16 v[98:101], v[176:179], v[198:201], v[98:101]
	v_mfma_f32_16x16x32_bf16 v[86:89], v[150:153], v[206:209], v[86:89]
	v_mfma_f32_16x16x32_bf16 v[82:85], v[176:179], v[206:209], v[82:85]
	v_mfma_f32_16x16x32_bf16 v[70:73], v[150:153], v[214:217], v[70:73]
	v_mfma_f32_16x16x32_bf16 v[66:69], v[176:179], v[214:217], v[66:69]
	s_setprio 0
	s_barrier
	s_add_i32 s26, s48, s33
	v_lshl_add_u64 v[158:159], v[158:159], 0, s[82:83]
	s_mov_b32 m0, s26
	ds_read_b128 v[180:183], v193 offset:49152
	ds_read_b128 v[184:187], v193 offset:50176
	ds_read_b128 v[194:197], v193 offset:51200
	ds_read_b128 v[198:201], v193 offset:52224
	ds_read_b128 v[202:205], v193 offset:53248
	ds_read_b128 v[206:209], v193 offset:54272
	ds_read_b128 v[210:213], v193 offset:55296
	ds_read_b128 v[214:217], v193 offset:56320
	global_load_lds_dwordx4 v[158:159], off
	s_add_i32 m0, s26, 0x2000
	s_add_u32 s24, s24, 0x40080
	v_lshl_add_u64 v[158:159], v[162:163], 0, s[82:83]
	s_addc_u32 s25, s25, 0
	s_add_i32 s26, s49, s33
	global_load_lds_dwordx4 v[158:159], off
	v_lshl_add_u64 v[158:159], s[24:25], 0, v[0:1]
	s_mov_b32 m0, s26
	s_nop 0
	global_load_lds_dwordx4 v[158:159], off
	v_lshl_add_u64 v[158:159], s[24:25], 0, v[154:155]
	s_add_i32 m0, s26, 0x2000
	s_nop 0
	global_load_lds_dwordx4 v[158:159], off
	v_lshl_add_u64 v[158:159], v[188:189], 0, s[82:83]
	s_mov_b32 m0, s38
	s_nop 0
	global_load_lds_dwordx4 v[158:159], off
	v_lshl_add_u64 v[158:159], v[218:219], 0, s[82:83]
	s_mov_b32 m0, s39
	s_nop 0
	global_load_lds_dwordx4 v[158:159], off
	s_waitcnt vmcnt(8)
	s_waitcnt lgkmcnt(0)
	s_barrier
	s_setprio 1
	v_mfma_f32_16x16x32_bf16 v[62:65], v[114:117], v[180:183], v[62:65]
	v_mfma_f32_16x16x32_bf16 v[58:61], v[122:125], v[180:183], v[58:61]
	v_mfma_f32_16x16x32_bf16 v[46:49], v[114:117], v[194:197], v[46:49]
	v_mfma_f32_16x16x32_bf16 v[42:45], v[122:125], v[194:197], v[42:45]
	v_mfma_f32_16x16x32_bf16 v[30:33], v[114:117], v[202:205], v[30:33]
	v_mfma_f32_16x16x32_bf16 v[26:29], v[122:125], v[202:205], v[26:29]
	v_mfma_f32_16x16x32_bf16 v[14:17], v[114:117], v[210:213], v[14:17]
	v_mfma_f32_16x16x32_bf16 v[10:13], v[122:125], v[210:213], v[10:13]
	v_mfma_f32_16x16x32_bf16 v[62:65], v[118:121], v[184:187], v[62:65]
	v_mfma_f32_16x16x32_bf16 v[58:61], v[134:137], v[184:187], v[58:61]
	v_mfma_f32_16x16x32_bf16 v[46:49], v[118:121], v[198:201], v[46:49]
	v_mfma_f32_16x16x32_bf16 v[42:45], v[134:137], v[198:201], v[42:45]
	v_mfma_f32_16x16x32_bf16 v[30:33], v[118:121], v[206:209], v[30:33]
	v_mfma_f32_16x16x32_bf16 v[26:29], v[134:137], v[206:209], v[26:29]
	v_mfma_f32_16x16x32_bf16 v[14:17], v[118:121], v[214:217], v[14:17]
	v_mfma_f32_16x16x32_bf16 v[10:13], v[134:137], v[214:217], v[10:13]
	s_setprio 0
	s_setprio 1
	v_mfma_f32_16x16x32_bf16 v[54:57], v[146:149], v[180:183], v[54:57]
	v_mfma_f32_16x16x32_bf16 v[50:53], v[172:175], v[180:183], v[50:53]
	v_mfma_f32_16x16x32_bf16 v[38:41], v[146:149], v[194:197], v[38:41]
	v_mfma_f32_16x16x32_bf16 v[34:37], v[172:175], v[194:197], v[34:37]
	v_mfma_f32_16x16x32_bf16 v[22:25], v[146:149], v[202:205], v[22:25]
	v_mfma_f32_16x16x32_bf16 v[18:21], v[172:175], v[202:205], v[18:21]
	v_mfma_f32_16x16x32_bf16 v[6:9], v[146:149], v[210:213], v[6:9]
	v_mfma_f32_16x16x32_bf16 v[2:5], v[172:175], v[210:213], v[2:5]
	v_mfma_f32_16x16x32_bf16 v[54:57], v[150:153], v[184:187], v[54:57]
	v_mfma_f32_16x16x32_bf16 v[50:53], v[176:179], v[184:187], v[50:53]
	v_mfma_f32_16x16x32_bf16 v[38:41], v[150:153], v[198:201], v[38:41]
	v_mfma_f32_16x16x32_bf16 v[34:37], v[176:179], v[198:201], v[34:37]
	v_mfma_f32_16x16x32_bf16 v[22:25], v[150:153], v[206:209], v[22:25]
	v_mfma_f32_16x16x32_bf16 v[18:21], v[176:179], v[206:209], v[18:21]
	v_mfma_f32_16x16x32_bf16 v[6:9], v[150:153], v[214:217], v[6:9]
	v_mfma_f32_16x16x32_bf16 v[2:5], v[176:179], v[214:217], v[2:5]
	s_setprio 0
	s_barrier
	s_add_i32 s47, s47, 2
	s_add_u32 s22, s22, 0x100
	s_addc_u32 s23, s23, 0
	s_add_u32 s45, s45, 0x100
	s_addc_u32 s46, s46, 0
	s_cmp_gt_u32 s47, 13
	s_cbranch_scc0 .LBB0_693
	s_and_b64 vcc, exec, s[12:13]
	s_cbranch_vccz .LBB0_696
	s_barrier

.LBB0_787:
	s_add_u32 s34, s8, 0x100
	s_addc_u32 s35, s9, 0
	s_and_b64 s[36:37], s[36:37], exec
	s_cselect_b32 s39, s64, s35
	s_cselect_b32 s38, s65, s34
	s_cselect_b32 s37, s25, s69
	s_cselect_b32 s36, s66, s68
	s_add_i32 s71, 0, 0x10000
	v_add_u32_e32 v0, s71, v228
	s_add_i32 s74, 0, 0x14000
	ds_read_b128 v[130:133], v0
	ds_read_b128 v[134:137], v0 offset:1024
	ds_read_b128 v[138:141], v0 offset:2048
	ds_read_b128 v[154:157], v0 offset:3072
	v_add_u32_e32 v0, s74, v228
	ds_read_b128 v[166:169], v0
	ds_read_b128 v[170:173], v0 offset:1024
	ds_read_b128 v[174:177], v0 offset:2048
	ds_read_b128 v[178:181], v0 offset:3072
	v_lshl_add_u64 v[158:159], s[8:9], 0, v[150:151]
	s_add_i32 m0, s52, 0xc000
	ds_read_b128 v[182:185], v233
	ds_read_b128 v[186:189], v233 offset:1024
	ds_read_b128 v[190:193], v233 offset:2048
	ds_read_b128 v[194:197], v233 offset:3072
	ds_read_b128 v[198:201], v233 offset:4096
	ds_read_b128 v[202:205], v233 offset:5120
	ds_read_b128 v[206:209], v233 offset:6144
	ds_read_b128 v[210:213], v233 offset:7168
	global_load_lds_dwordx4 v[158:159], off
	v_lshl_add_u64 v[158:159], s[8:9], 0, v[152:153]
	s_add_i32 m0, s52, 0xe000
	s_nop 0
	global_load_lds_dwordx4 v[158:159], off
	s_waitcnt vmcnt(8)
	s_waitcnt lgkmcnt(0)
	s_barrier
	s_setprio 1
	v_mfma_f32_16x16x32_bf16 v[118:121], v[130:133], v[182:185], v[118:121]
	v_mfma_f32_16x16x32_bf16 v[54:57], v[138:141], v[182:185], v[54:57]
	v_mfma_f32_16x16x32_bf16 v[114:117], v[130:133], v[190:193], v[114:117]
	v_mfma_f32_16x16x32_bf16 v[50:53], v[138:141], v[190:193], v[50:53]
	v_mfma_f32_16x16x32_bf16 v[126:129], v[130:133], v[198:201], v[126:129]
	v_mfma_f32_16x16x32_bf16 v[62:65], v[138:141], v[198:201], v[62:65]
	v_mfma_f32_16x16x32_bf16 v[122:125], v[130:133], v[206:209], v[122:125]
	v_mfma_f32_16x16x32_bf16 v[58:61], v[138:141], v[206:209], v[58:61]
	v_mfma_f32_16x16x32_bf16 v[118:121], v[134:137], v[186:189], v[118:121]
	v_mfma_f32_16x16x32_bf16 v[54:57], v[154:157], v[186:189], v[54:57]
	v_mfma_f32_16x16x32_bf16 v[114:117], v[134:137], v[194:197], v[114:117]
	v_mfma_f32_16x16x32_bf16 v[50:53], v[154:157], v[194:197], v[50:53]
	v_mfma_f32_16x16x32_bf16 v[126:129], v[134:137], v[202:205], v[126:129]
	v_mfma_f32_16x16x32_bf16 v[62:65], v[154:157], v[202:205], v[62:65]
	v_mfma_f32_16x16x32_bf16 v[122:125], v[134:137], v[210:213], v[122:125]
	v_mfma_f32_16x16x32_bf16 v[58:61], v[154:157], v[210:213], v[58:61]
	s_setprio 0
	s_setprio 1
	v_mfma_f32_16x16x32_bf16 v[102:105], v[166:169], v[182:185], v[102:105]
	v_mfma_f32_16x16x32_bf16 v[38:41], v[174:177], v[182:185], v[38:41]
	v_mfma_f32_16x16x32_bf16 v[98:101], v[166:169], v[190:193], v[98:101]
	v_mfma_f32_16x16x32_bf16 v[34:37], v[174:177], v[190:193], v[34:37]
	v_mfma_f32_16x16x32_bf16 v[110:113], v[166:169], v[198:201], v[110:113]
	v_mfma_f32_16x16x32_bf16 v[46:49], v[174:177], v[198:201], v[46:49]
	v_mfma_f32_16x16x32_bf16 v[106:109], v[166:169], v[206:209], v[106:109]
	v_mfma_f32_16x16x32_bf16 v[42:45], v[174:177], v[206:209], v[42:45]
	v_mfma_f32_16x16x32_bf16 v[102:105], v[170:173], v[186:189], v[102:105]
	v_mfma_f32_16x16x32_bf16 v[38:41], v[178:181], v[186:189], v[38:41]
	v_mfma_f32_16x16x32_bf16 v[98:101], v[170:173], v[194:197], v[98:101]
	v_mfma_f32_16x16x32_bf16 v[34:37], v[178:181], v[194:197], v[34:37]
	v_mfma_f32_16x16x32_bf16 v[110:113], v[170:173], v[202:205], v[110:113]
	v_mfma_f32_16x16x32_bf16 v[46:49], v[178:181], v[202:205], v[46:49]
	v_mfma_f32_16x16x32_bf16 v[106:109], v[170:173], v[210:213], v[106:109]
	v_mfma_f32_16x16x32_bf16 v[42:45], v[178:181], v[210:213], v[42:45]
	s_setprio 0
	s_barrier
	s_add_i32 s8, s71, s51
	v_lshl_add_u64 v[158:159], s[36:37], 0, v[144:145]
	s_mov_b32 m0, s8
	ds_read_b128 v[182:185], v233 offset:16384
	ds_read_b128 v[186:189], v233 offset:17408
	ds_read_b128 v[190:193], v233 offset:18432
	ds_read_b128 v[194:197], v233 offset:19456
	ds_read_b128 v[198:201], v233 offset:20480
	ds_read_b128 v[202:205], v233 offset:21504
	ds_read_b128 v[206:209], v233 offset:22528
	ds_read_b128 v[210:213], v233 offset:23552
	global_load_lds_dwordx4 v[158:159], off
	s_add_i32 m0, s8, 0x2000
	s_add_u32 s8, s36, 0x40000
	v_lshl_add_u64 v[162:163], s[36:37], 0, v[148:149]
	s_addc_u32 s9, s37, 0
	s_add_i32 s71, s74, s51
	global_load_lds_dwordx4 v[162:163], off
	v_lshl_add_u64 v[214:215], s[8:9], 0, v[144:145]
	s_mov_b32 m0, s71
	v_lshl_add_u64 v[216:217], s[38:39], 0, v[146:147]
	global_load_lds_dwordx4 v[214:215], off
	v_lshl_add_u64 v[214:215], s[8:9], 0, v[148:149]
	s_add_i32 m0, s71, 0x2000
	s_nop 0
	global_load_lds_dwordx4 v[214:215], off
	v_lshl_add_u64 v[214:215], s[38:39], 0, v[142:143]
	s_mov_b32 m0, s52
	s_nop 0
	global_load_lds_dwordx4 v[214:215], off
	s_mov_b32 m0, s53
	s_nop 0
	global_load_lds_dwordx4 v[216:217], off
	s_waitcnt vmcnt(8)
	s_waitcnt lgkmcnt(0)
	s_barrier
	s_setprio 1
	v_mfma_f32_16x16x32_bf16 v[86:89], v[130:133], v[182:185], v[86:89]
	v_mfma_f32_16x16x32_bf16 v[22:25], v[138:141], v[182:185], v[22:25]
	v_mfma_f32_16x16x32_bf16 v[82:85], v[130:133], v[190:193], v[82:85]
	v_mfma_f32_16x16x32_bf16 v[18:21], v[138:141], v[190:193], v[18:21]
	v_mfma_f32_16x16x32_bf16 v[94:97], v[130:133], v[198:201], v[94:97]
	v_mfma_f32_16x16x32_bf16 v[30:33], v[138:141], v[198:201], v[30:33]
	v_mfma_f32_16x16x32_bf16 v[90:93], v[130:133], v[206:209], v[90:93]
	v_mfma_f32_16x16x32_bf16 v[26:29], v[138:141], v[206:209], v[26:29]
	v_mfma_f32_16x16x32_bf16 v[86:89], v[134:137], v[186:189], v[86:89]
	v_mfma_f32_16x16x32_bf16 v[22:25], v[154:157], v[186:189], v[22:25]
	v_mfma_f32_16x16x32_bf16 v[82:85], v[134:137], v[194:197], v[82:85]
	v_mfma_f32_16x16x32_bf16 v[18:21], v[154:157], v[194:197], v[18:21]
	v_mfma_f32_16x16x32_bf16 v[94:97], v[134:137], v[202:205], v[94:97]
	v_mfma_f32_16x16x32_bf16 v[30:33], v[154:157], v[202:205], v[30:33]
	v_mfma_f32_16x16x32_bf16 v[90:93], v[134:137], v[210:213], v[90:93]
	v_mfma_f32_16x16x32_bf16 v[26:29], v[154:157], v[210:213], v[26:29]
	s_setprio 0
	s_setprio 1
	v_mfma_f32_16x16x32_bf16 v[70:73], v[166:169], v[182:185], v[70:73]
	v_mfma_f32_16x16x32_bf16 v[6:9], v[174:177], v[182:185], v[6:9]
	v_mfma_f32_16x16x32_bf16 v[66:69], v[166:169], v[190:193], v[66:69]
	v_mfma_f32_16x16x32_bf16 v[2:5], v[174:177], v[190:193], v[2:5]
	v_mfma_f32_16x16x32_bf16 v[78:81], v[166:169], v[198:201], v[78:81]
	v_mfma_f32_16x16x32_bf16 v[14:17], v[174:177], v[198:201], v[14:17]
	v_mfma_f32_16x16x32_bf16 v[74:77], v[166:169], v[206:209], v[74:77]
	v_mfma_f32_16x16x32_bf16 v[10:13], v[174:177], v[206:209], v[10:13]
	v_mfma_f32_16x16x32_bf16 v[70:73], v[170:173], v[186:189], v[70:73]
	v_mfma_f32_16x16x32_bf16 v[6:9], v[178:181], v[186:189], v[6:9]
	v_mfma_f32_16x16x32_bf16 v[66:69], v[170:173], v[194:197], v[66:69]
	v_mfma_f32_16x16x32_bf16 v[2:5], v[178:181], v[194:197], v[2:5]
	v_mfma_f32_16x16x32_bf16 v[78:81], v[170:173], v[202:205], v[78:81]
	v_mfma_f32_16x16x32_bf16 v[14:17], v[178:181], v[202:205], v[14:17]
	v_mfma_f32_16x16x32_bf16 v[74:77], v[170:173], v[210:213], v[74:77]
	v_mfma_f32_16x16x32_bf16 v[10:13], v[178:181], v[210:213], v[10:13]
	s_setprio 0
	s_barrier
	s_add_i32 s71, 0, 0x18000
	v_add_u32_e32 v0, s71, v228
	s_add_i32 s74, 0, 0x1c000
	ds_read_b128 v[130:133], v0
	ds_read_b128 v[134:137], v0 offset:1024
	ds_read_b128 v[138:141], v0 offset:2048
	ds_read_b128 v[154:157], v0 offset:3072
	v_add_u32_e32 v0, s74, v228
	ds_read_b128 v[166:169], v0
	ds_read_b128 v[170:173], v0 offset:1024
	ds_read_b128 v[174:177], v0 offset:2048
	ds_read_b128 v[178:181], v0 offset:3072
	s_add_u32 s8, s38, 0x40000
	s_addc_u32 s9, s39, 0
	s_mov_b32 m0, s54
	v_lshl_add_u64 v[218:219], s[8:9], 0, v[142:143]
	ds_read_b128 v[182:185], v233 offset:32768
	ds_read_b128 v[186:189], v233 offset:33792
	ds_read_b128 v[190:193], v233 offset:34816
	ds_read_b128 v[194:197], v233 offset:35840
	ds_read_b128 v[198:201], v233 offset:36864
	ds_read_b128 v[202:205], v233 offset:37888
	ds_read_b128 v[206:209], v233 offset:38912
	ds_read_b128 v[210:213], v233 offset:39936
	global_load_lds_dwordx4 v[218:219], off
	v_lshl_add_u64 v[218:219], s[8:9], 0, v[146:147]
	s_mov_b32 m0, s55
	s_nop 0
	global_load_lds_dwordx4 v[218:219], off
	s_waitcnt vmcnt(8)
	s_waitcnt lgkmcnt(0)
	s_barrier
	s_setprio 1
	v_mfma_f32_16x16x32_bf16 v[118:121], v[130:133], v[182:185], v[118:121]
	v_mfma_f32_16x16x32_bf16 v[54:57], v[138:141], v[182:185], v[54:57]
	v_mfma_f32_16x16x32_bf16 v[114:117], v[130:133], v[190:193], v[114:117]
	v_mfma_f32_16x16x32_bf16 v[50:53], v[138:141], v[190:193], v[50:53]
	v_mfma_f32_16x16x32_bf16 v[126:129], v[130:133], v[198:201], v[126:129]
	v_mfma_f32_16x16x32_bf16 v[62:65], v[138:141], v[198:201], v[62:65]
	v_mfma_f32_16x16x32_bf16 v[122:125], v[130:133], v[206:209], v[122:125]
	v_mfma_f32_16x16x32_bf16 v[58:61], v[138:141], v[206:209], v[58:61]
	v_mfma_f32_16x16x32_bf16 v[118:121], v[134:137], v[186:189], v[118:121]
	v_mfma_f32_16x16x32_bf16 v[54:57], v[154:157], v[186:189], v[54:57]
	v_mfma_f32_16x16x32_bf16 v[114:117], v[134:137], v[194:197], v[114:117]
	v_mfma_f32_16x16x32_bf16 v[50:53], v[154:157], v[194:197], v[50:53]
	v_mfma_f32_16x16x32_bf16 v[126:129], v[134:137], v[202:205], v[126:129]
	v_mfma_f32_16x16x32_bf16 v[62:65], v[154:157], v[202:205], v[62:65]
	v_mfma_f32_16x16x32_bf16 v[122:125], v[134:137], v[210:213], v[122:125]
	v_mfma_f32_16x16x32_bf16 v[58:61], v[154:157], v[210:213], v[58:61]
	s_setprio 0
	s_setprio 1
	v_mfma_f32_16x16x32_bf16 v[102:105], v[166:169], v[182:185], v[102:105]
	v_mfma_f32_16x16x32_bf16 v[38:41], v[174:177], v[182:185], v[38:41]
	v_mfma_f32_16x16x32_bf16 v[98:101], v[166:169], v[190:193], v[98:101]
	v_mfma_f32_16x16x32_bf16 v[34:37], v[174:177], v[190:193], v[34:37]
	v_mfma_f32_16x16x32_bf16 v[110:113], v[166:169], v[198:201], v[110:113]
	v_mfma_f32_16x16x32_bf16 v[46:49], v[174:177], v[198:201], v[46:49]
	v_mfma_f32_16x16x32_bf16 v[106:109], v[166:169], v[206:209], v[106:109]
	v_mfma_f32_16x16x32_bf16 v[42:45], v[174:177], v[206:209], v[42:45]
	v_mfma_f32_16x16x32_bf16 v[102:105], v[170:173], v[186:189], v[102:105]
	v_mfma_f32_16x16x32_bf16 v[38:41], v[178:181], v[186:189], v[38:41]
	v_mfma_f32_16x16x32_bf16 v[98:101], v[170:173], v[194:197], v[98:101]
	v_mfma_f32_16x16x32_bf16 v[34:37], v[178:181], v[194:197], v[34:37]
	v_mfma_f32_16x16x32_bf16 v[110:113], v[170:173], v[202:205], v[110:113]
	v_mfma_f32_16x16x32_bf16 v[46:49], v[178:181], v[202:205], v[46:49]
	v_mfma_f32_16x16x32_bf16 v[106:109], v[170:173], v[210:213], v[106:109]
	v_mfma_f32_16x16x32_bf16 v[42:45], v[178:181], v[210:213], v[42:45]
	s_setprio 0
	s_barrier
	s_add_i32 s8, s71, s51
	v_lshl_add_u64 v[158:159], v[158:159], 0, s[82:83]
	s_mov_b32 m0, s8
	ds_read_b128 v[182:185], v233 offset:49152
	ds_read_b128 v[186:189], v233 offset:50176
	ds_read_b128 v[190:193], v233 offset:51200
	ds_read_b128 v[194:197], v233 offset:52224
	ds_read_b128 v[198:201], v233 offset:53248
	ds_read_b128 v[202:205], v233 offset:54272
	ds_read_b128 v[206:209], v233 offset:55296
	ds_read_b128 v[210:213], v233 offset:56320
	global_load_lds_dwordx4 v[158:159], off
	s_add_i32 m0, s8, 0x2000
	s_add_u32 s8, s36, 0x40080
	v_lshl_add_u64 v[158:159], v[162:163], 0, s[82:83]
	s_addc_u32 s9, s37, 0
	s_add_i32 s36, s74, s51
	global_load_lds_dwordx4 v[158:159], off
	v_lshl_add_u64 v[158:159], s[8:9], 0, v[144:145]
	s_mov_b32 m0, s36
	s_nop 0
	global_load_lds_dwordx4 v[158:159], off
	v_lshl_add_u64 v[158:159], s[8:9], 0, v[148:149]
	s_add_i32 m0, s36, 0x2000
	s_nop 0
	global_load_lds_dwordx4 v[158:159], off
	v_lshl_add_u64 v[158:159], v[214:215], 0, s[82:83]
	s_mov_b32 m0, s58
	s_nop 0
	global_load_lds_dwordx4 v[158:159], off
	v_lshl_add_u64 v[158:159], v[216:217], 0, s[82:83]
	s_mov_b32 m0, s59
	s_nop 0
	global_load_lds_dwordx4 v[158:159], off
	s_waitcnt vmcnt(8)
	s_waitcnt lgkmcnt(0)
	s_barrier
	s_setprio 1
	v_mfma_f32_16x16x32_bf16 v[86:89], v[130:133], v[182:185], v[86:89]
	v_mfma_f32_16x16x32_bf16 v[22:25], v[138:141], v[182:185], v[22:25]
	v_mfma_f32_16x16x32_bf16 v[82:85], v[130:133], v[190:193], v[82:85]
	v_mfma_f32_16x16x32_bf16 v[18:21], v[138:141], v[190:193], v[18:21]
	v_mfma_f32_16x16x32_bf16 v[94:97], v[130:133], v[198:201], v[94:97]
	v_mfma_f32_16x16x32_bf16 v[30:33], v[138:141], v[198:201], v[30:33]
	v_mfma_f32_16x16x32_bf16 v[90:93], v[130:133], v[206:209], v[90:93]
	v_mfma_f32_16x16x32_bf16 v[26:29], v[138:141], v[206:209], v[26:29]
	v_mfma_f32_16x16x32_bf16 v[86:89], v[134:137], v[186:189], v[86:89]
	v_mfma_f32_16x16x32_bf16 v[22:25], v[154:157], v[186:189], v[22:25]
	v_mfma_f32_16x16x32_bf16 v[82:85], v[134:137], v[194:197], v[82:85]
	v_mfma_f32_16x16x32_bf16 v[18:21], v[154:157], v[194:197], v[18:21]
	v_mfma_f32_16x16x32_bf16 v[94:97], v[134:137], v[202:205], v[94:97]
	v_mfma_f32_16x16x32_bf16 v[30:33], v[154:157], v[202:205], v[30:33]
	v_mfma_f32_16x16x32_bf16 v[90:93], v[134:137], v[210:213], v[90:93]
	v_mfma_f32_16x16x32_bf16 v[26:29], v[154:157], v[210:213], v[26:29]
	s_setprio 0
	s_setprio 1
	v_mfma_f32_16x16x32_bf16 v[70:73], v[166:169], v[182:185], v[70:73]
	v_mfma_f32_16x16x32_bf16 v[6:9], v[174:177], v[182:185], v[6:9]
	v_mfma_f32_16x16x32_bf16 v[66:69], v[166:169], v[190:193], v[66:69]
	v_mfma_f32_16x16x32_bf16 v[2:5], v[174:177], v[190:193], v[2:5]
	v_mfma_f32_16x16x32_bf16 v[78:81], v[166:169], v[198:201], v[78:81]
	v_mfma_f32_16x16x32_bf16 v[14:17], v[174:177], v[198:201], v[14:17]
	v_mfma_f32_16x16x32_bf16 v[74:77], v[166:169], v[206:209], v[74:77]
	v_mfma_f32_16x16x32_bf16 v[10:13], v[174:177], v[206:209], v[10:13]
	v_mfma_f32_16x16x32_bf16 v[70:73], v[170:173], v[186:189], v[70:73]
	v_mfma_f32_16x16x32_bf16 v[6:9], v[178:181], v[186:189], v[6:9]
	v_mfma_f32_16x16x32_bf16 v[66:69], v[170:173], v[194:197], v[66:69]
	v_mfma_f32_16x16x32_bf16 v[2:5], v[178:181], v[194:197], v[2:5]
	v_mfma_f32_16x16x32_bf16 v[78:81], v[170:173], v[202:205], v[78:81]
	v_mfma_f32_16x16x32_bf16 v[14:17], v[178:181], v[202:205], v[14:17]
	v_mfma_f32_16x16x32_bf16 v[74:77], v[170:173], v[210:213], v[74:77]
	v_mfma_f32_16x16x32_bf16 v[10:13], v[178:181], v[210:213], v[10:13]
	s_setprio 0
	s_barrier
	s_add_i32 s70, s70, 2
	s_add_u32 s68, s68, 0x100
	s_addc_u32 s69, s69, 0
	s_cmp_gt_u32 s70, 13
	s_cbranch_scc1 .LBB0_789
	s_mov_b64 s[8:9], s[34:35]
	s_branch .LBB0_782

.LBB0_966:
	s_add_u32 s20, s18, 0x100
	s_addc_u32 s21, s19, 0
	s_add_i32 s46, 0, 0x10000
	s_cmp_eq_u32 s45, 40
	s_cselect_b32 s25, s9, s21
	s_cselect_b32 s24, s8, s20
	s_cselect_b32 s23, s17, s44
	s_cselect_b32 s22, s16, s43
	s_add_i32 s47, 0, 0x14000
	v_add_u32_e32 v134, s46, v191
	v_add_u32_e32 v158, s47, v191
	ds_read_b128 v[114:117], v134
	ds_read_b128 v[118:121], v134 offset:1024
	ds_read_b128 v[122:125], v134 offset:2048
	ds_read_b128 v[134:137], v134 offset:3072
	ds_read_b128 v[146:149], v158
	ds_read_b128 v[150:153], v158 offset:1024
	ds_read_b128 v[172:175], v158 offset:2048
	ds_read_b128 v[176:179], v158 offset:3072
	v_lshl_add_u64 v[158:159], s[18:19], 0, v[168:169]
	s_add_i32 m0, s31, 0xc000
	ds_read_b128 v[180:183], v193
	ds_read_b128 v[184:187], v193 offset:1024
	ds_read_b128 v[194:197], v193 offset:2048
	ds_read_b128 v[198:201], v193 offset:3072
	ds_read_b128 v[202:205], v193 offset:4096
	ds_read_b128 v[206:209], v193 offset:5120
	ds_read_b128 v[210:213], v193 offset:6144
	ds_read_b128 v[214:217], v193 offset:7168
	global_load_lds_dwordx4 v[158:159], off
	v_lshl_add_u64 v[158:159], s[18:19], 0, v[170:171]
	s_add_i32 m0, s31, 0xe000
	s_nop 0
	global_load_lds_dwordx4 v[158:159], off
	s_waitcnt vmcnt(8)
	s_waitcnt lgkmcnt(0)
	s_barrier
	s_setprio 1
	v_mfma_f32_16x16x32_bf16 v[142:145], v[114:117], v[180:183], v[142:145]
	v_mfma_f32_16x16x32_bf16 v[138:141], v[122:125], v[180:183], v[138:141]
	v_mfma_f32_16x16x32_bf16 v[110:113], v[114:117], v[194:197], v[110:113]
	v_mfma_f32_16x16x32_bf16 v[106:109], v[122:125], v[194:197], v[106:109]
	v_mfma_f32_16x16x32_bf16 v[94:97], v[114:117], v[202:205], v[94:97]
	v_mfma_f32_16x16x32_bf16 v[90:93], v[122:125], v[202:205], v[90:93]
	v_mfma_f32_16x16x32_bf16 v[78:81], v[114:117], v[210:213], v[78:81]
	v_mfma_f32_16x16x32_bf16 v[74:77], v[122:125], v[210:213], v[74:77]
	v_mfma_f32_16x16x32_bf16 v[142:145], v[118:121], v[184:187], v[142:145]
	v_mfma_f32_16x16x32_bf16 v[138:141], v[134:137], v[184:187], v[138:141]
	v_mfma_f32_16x16x32_bf16 v[110:113], v[118:121], v[198:201], v[110:113]
	v_mfma_f32_16x16x32_bf16 v[106:109], v[134:137], v[198:201], v[106:109]
	v_mfma_f32_16x16x32_bf16 v[94:97], v[118:121], v[206:209], v[94:97]
	v_mfma_f32_16x16x32_bf16 v[90:93], v[134:137], v[206:209], v[90:93]
	v_mfma_f32_16x16x32_bf16 v[78:81], v[118:121], v[214:217], v[78:81]
	v_mfma_f32_16x16x32_bf16 v[74:77], v[134:137], v[214:217], v[74:77]
	s_setprio 0
	s_setprio 1
	v_mfma_f32_16x16x32_bf16 v[130:133], v[146:149], v[180:183], v[130:133]
	v_mfma_f32_16x16x32_bf16 v[126:129], v[172:175], v[180:183], v[126:129]
	v_mfma_f32_16x16x32_bf16 v[102:105], v[146:149], v[194:197], v[102:105]
	v_mfma_f32_16x16x32_bf16 v[98:101], v[172:175], v[194:197], v[98:101]
	v_mfma_f32_16x16x32_bf16 v[86:89], v[146:149], v[202:205], v[86:89]
	v_mfma_f32_16x16x32_bf16 v[82:85], v[172:175], v[202:205], v[82:85]
	v_mfma_f32_16x16x32_bf16 v[70:73], v[146:149], v[210:213], v[70:73]
	v_mfma_f32_16x16x32_bf16 v[66:69], v[172:175], v[210:213], v[66:69]
	v_mfma_f32_16x16x32_bf16 v[130:133], v[150:153], v[184:187], v[130:133]
	v_mfma_f32_16x16x32_bf16 v[126:129], v[176:179], v[184:187], v[126:129]
	v_mfma_f32_16x16x32_bf16 v[102:105], v[150:153], v[198:201], v[102:105]
	v_mfma_f32_16x16x32_bf16 v[98:101], v[176:179], v[198:201], v[98:101]
	v_mfma_f32_16x16x32_bf16 v[86:89], v[150:153], v[206:209], v[86:89]
	v_mfma_f32_16x16x32_bf16 v[82:85], v[176:179], v[206:209], v[82:85]
	v_mfma_f32_16x16x32_bf16 v[70:73], v[150:153], v[214:217], v[70:73]
	v_mfma_f32_16x16x32_bf16 v[66:69], v[176:179], v[214:217], v[66:69]
	s_setprio 0
	s_barrier
	s_add_i32 s18, s46, s30
	v_lshl_add_u64 v[158:159], s[22:23], 0, v[0:1]
	s_mov_b32 m0, s18
	ds_read_b128 v[180:183], v193 offset:16384
	ds_read_b128 v[184:187], v193 offset:17408
	ds_read_b128 v[194:197], v193 offset:18432
	ds_read_b128 v[198:201], v193 offset:19456
	ds_read_b128 v[202:205], v193 offset:20480
	ds_read_b128 v[206:209], v193 offset:21504
	ds_read_b128 v[210:213], v193 offset:22528
	ds_read_b128 v[214:217], v193 offset:23552
	global_load_lds_dwordx4 v[158:159], off
	s_add_i32 m0, s18, 0x2000
	s_add_u32 s18, s22, 0xb0000
	v_lshl_add_u64 v[162:163], s[22:23], 0, v[154:155]
	s_addc_u32 s19, s23, 0
	s_add_i32 s46, s47, s30
	global_load_lds_dwordx4 v[162:163], off
	v_lshl_add_u64 v[188:189], s[18:19], 0, v[0:1]
	s_mov_b32 m0, s46
	v_lshl_add_u64 v[218:219], s[24:25], 0, v[156:157]
	global_load_lds_dwordx4 v[188:189], off
	v_lshl_add_u64 v[188:189], s[18:19], 0, v[154:155]
	s_add_i32 m0, s46, 0x2000
	s_nop 0
	global_load_lds_dwordx4 v[188:189], off
	v_lshl_add_u64 v[188:189], s[24:25], 0, v[166:167]
	s_mov_b32 m0, s31
	s_nop 0
	global_load_lds_dwordx4 v[188:189], off
	s_mov_b32 m0, s33
	s_nop 0
	global_load_lds_dwordx4 v[218:219], off
	s_waitcnt vmcnt(8)
	s_waitcnt lgkmcnt(0)
	s_barrier
	s_setprio 1
	v_mfma_f32_16x16x32_bf16 v[62:65], v[114:117], v[180:183], v[62:65]
	v_mfma_f32_16x16x32_bf16 v[58:61], v[122:125], v[180:183], v[58:61]
	v_mfma_f32_16x16x32_bf16 v[46:49], v[114:117], v[194:197], v[46:49]
	v_mfma_f32_16x16x32_bf16 v[42:45], v[122:125], v[194:197], v[42:45]
	v_mfma_f32_16x16x32_bf16 v[30:33], v[114:117], v[202:205], v[30:33]
	v_mfma_f32_16x16x32_bf16 v[26:29], v[122:125], v[202:205], v[26:29]
	v_mfma_f32_16x16x32_bf16 v[14:17], v[114:117], v[210:213], v[14:17]
	v_mfma_f32_16x16x32_bf16 v[10:13], v[122:125], v[210:213], v[10:13]
	v_mfma_f32_16x16x32_bf16 v[62:65], v[118:121], v[184:187], v[62:65]
	v_mfma_f32_16x16x32_bf16 v[58:61], v[134:137], v[184:187], v[58:61]
	v_mfma_f32_16x16x32_bf16 v[46:49], v[118:121], v[198:201], v[46:49]
	v_mfma_f32_16x16x32_bf16 v[42:45], v[134:137], v[198:201], v[42:45]
	v_mfma_f32_16x16x32_bf16 v[30:33], v[118:121], v[206:209], v[30:33]
	v_mfma_f32_16x16x32_bf16 v[26:29], v[134:137], v[206:209], v[26:29]
	v_mfma_f32_16x16x32_bf16 v[14:17], v[118:121], v[214:217], v[14:17]
	v_mfma_f32_16x16x32_bf16 v[10:13], v[134:137], v[214:217], v[10:13]
	s_setprio 0
	s_setprio 1
	v_mfma_f32_16x16x32_bf16 v[54:57], v[146:149], v[180:183], v[54:57]
	v_mfma_f32_16x16x32_bf16 v[50:53], v[172:175], v[180:183], v[50:53]
	v_mfma_f32_16x16x32_bf16 v[38:41], v[146:149], v[194:197], v[38:41]
	v_mfma_f32_16x16x32_bf16 v[34:37], v[172:175], v[194:197], v[34:37]
	v_mfma_f32_16x16x32_bf16 v[22:25], v[146:149], v[202:205], v[22:25]
	v_mfma_f32_16x16x32_bf16 v[18:21], v[172:175], v[202:205], v[18:21]
	v_mfma_f32_16x16x32_bf16 v[6:9], v[146:149], v[210:213], v[6:9]
	v_mfma_f32_16x16x32_bf16 v[2:5], v[172:175], v[210:213], v[2:5]
	v_mfma_f32_16x16x32_bf16 v[54:57], v[150:153], v[184:187], v[54:57]
	v_mfma_f32_16x16x32_bf16 v[50:53], v[176:179], v[184:187], v[50:53]
	v_mfma_f32_16x16x32_bf16 v[38:41], v[150:153], v[198:201], v[38:41]
	v_mfma_f32_16x16x32_bf16 v[34:37], v[176:179], v[198:201], v[34:37]
	v_mfma_f32_16x16x32_bf16 v[22:25], v[150:153], v[206:209], v[22:25]
	v_mfma_f32_16x16x32_bf16 v[18:21], v[176:179], v[206:209], v[18:21]
	v_mfma_f32_16x16x32_bf16 v[6:9], v[150:153], v[214:217], v[6:9]
	v_mfma_f32_16x16x32_bf16 v[2:5], v[176:179], v[214:217], v[2:5]
	s_setprio 0
	s_barrier
	s_add_i32 s46, 0, 0x18000
	s_add_i32 s47, 0, 0x1c000
	v_add_u32_e32 v134, s46, v191
	v_add_u32_e32 v176, s47, v191
	ds_read_b128 v[114:117], v134
	ds_read_b128 v[118:121], v134 offset:1024
	ds_read_b128 v[122:125], v134 offset:2048
	ds_read_b128 v[134:137], v134 offset:3072
	ds_read_b128 v[146:149], v176
	ds_read_b128 v[150:153], v176 offset:1024
	ds_read_b128 v[172:175], v176 offset:2048
	ds_read_b128 v[176:179], v176 offset:3072
	s_add_u32 s18, s24, 0xb0000
	s_addc_u32 s19, s25, 0
	s_mov_b32 m0, s34
	v_lshl_add_u64 v[220:221], s[18:19], 0, v[166:167]
	ds_read_b128 v[180:183], v193 offset:32768
	ds_read_b128 v[184:187], v193 offset:33792
	ds_read_b128 v[194:197], v193 offset:34816
	ds_read_b128 v[198:201], v193 offset:35840
	ds_read_b128 v[202:205], v193 offset:36864
	ds_read_b128 v[206:209], v193 offset:37888
	ds_read_b128 v[210:213], v193 offset:38912
	ds_read_b128 v[214:217], v193 offset:39936
	global_load_lds_dwordx4 v[220:221], off
	v_lshl_add_u64 v[220:221], s[18:19], 0, v[156:157]
	s_mov_b32 m0, s35
	s_nop 0
	global_load_lds_dwordx4 v[220:221], off
	s_waitcnt vmcnt(8)
	s_waitcnt lgkmcnt(0)
	s_barrier
	s_setprio 1
	v_mfma_f32_16x16x32_bf16 v[142:145], v[114:117], v[180:183], v[142:145]
	v_mfma_f32_16x16x32_bf16 v[138:141], v[122:125], v[180:183], v[138:141]
	v_mfma_f32_16x16x32_bf16 v[110:113], v[114:117], v[194:197], v[110:113]
	v_mfma_f32_16x16x32_bf16 v[106:109], v[122:125], v[194:197], v[106:109]
	v_mfma_f32_16x16x32_bf16 v[94:97], v[114:117], v[202:205], v[94:97]
	v_mfma_f32_16x16x32_bf16 v[90:93], v[122:125], v[202:205], v[90:93]
	v_mfma_f32_16x16x32_bf16 v[78:81], v[114:117], v[210:213], v[78:81]
	v_mfma_f32_16x16x32_bf16 v[74:77], v[122:125], v[210:213], v[74:77]
	v_mfma_f32_16x16x32_bf16 v[142:145], v[118:121], v[184:187], v[142:145]
	v_mfma_f32_16x16x32_bf16 v[138:141], v[134:137], v[184:187], v[138:141]
	v_mfma_f32_16x16x32_bf16 v[110:113], v[118:121], v[198:201], v[110:113]
	v_mfma_f32_16x16x32_bf16 v[106:109], v[134:137], v[198:201], v[106:109]
	v_mfma_f32_16x16x32_bf16 v[94:97], v[118:121], v[206:209], v[94:97]
	v_mfma_f32_16x16x32_bf16 v[90:93], v[134:137], v[206:209], v[90:93]
	v_mfma_f32_16x16x32_bf16 v[78:81], v[118:121], v[214:217], v[78:81]
	v_mfma_f32_16x16x32_bf16 v[74:77], v[134:137], v[214:217], v[74:77]
	s_setprio 0
	s_setprio 1
	v_mfma_f32_16x16x32_bf16 v[130:133], v[146:149], v[180:183], v[130:133]
	v_mfma_f32_16x16x32_bf16 v[126:129], v[172:175], v[180:183], v[126:129]
	v_mfma_f32_16x16x32_bf16 v[102:105], v[146:149], v[194:197], v[102:105]
	v_mfma_f32_16x16x32_bf16 v[98:101], v[172:175], v[194:197], v[98:101]
	v_mfma_f32_16x16x32_bf16 v[86:89], v[146:149], v[202:205], v[86:89]
	v_mfma_f32_16x16x32_bf16 v[82:85], v[172:175], v[202:205], v[82:85]
	v_mfma_f32_16x16x32_bf16 v[70:73], v[146:149], v[210:213], v[70:73]
	v_mfma_f32_16x16x32_bf16 v[66:69], v[172:175], v[210:213], v[66:69]
	v_mfma_f32_16x16x32_bf16 v[130:133], v[150:153], v[184:187], v[130:133]
	v_mfma_f32_16x16x32_bf16 v[126:129], v[176:179], v[184:187], v[126:129]
	v_mfma_f32_16x16x32_bf16 v[102:105], v[150:153], v[198:201], v[102:105]
	v_mfma_f32_16x16x32_bf16 v[98:101], v[176:179], v[198:201], v[98:101]
	v_mfma_f32_16x16x32_bf16 v[86:89], v[150:153], v[206:209], v[86:89]
	v_mfma_f32_16x16x32_bf16 v[82:85], v[176:179], v[206:209], v[82:85]
	v_mfma_f32_16x16x32_bf16 v[70:73], v[150:153], v[214:217], v[70:73]
	v_mfma_f32_16x16x32_bf16 v[66:69], v[176:179], v[214:217], v[66:69]
	s_setprio 0
	s_barrier
	s_add_i32 s18, s46, s30
	v_lshl_add_u64 v[158:159], v[158:159], 0, s[82:83]
	s_mov_b32 m0, s18
	ds_read_b128 v[180:183], v193 offset:49152
	ds_read_b128 v[184:187], v193 offset:50176
	ds_read_b128 v[194:197], v193 offset:51200
	ds_read_b128 v[198:201], v193 offset:52224
	ds_read_b128 v[202:205], v193 offset:53248
	ds_read_b128 v[206:209], v193 offset:54272
	ds_read_b128 v[210:213], v193 offset:55296
	ds_read_b128 v[214:217], v193 offset:56320
	global_load_lds_dwordx4 v[158:159], off
	s_add_i32 m0, s18, 0x2000
	s_add_u32 s18, s22, 0xb0080
	v_lshl_add_u64 v[158:159], v[162:163], 0, s[82:83]
	s_addc_u32 s19, s23, 0
	s_add_i32 s22, s47, s30
	global_load_lds_dwordx4 v[158:159], off
	v_lshl_add_u64 v[158:159], s[18:19], 0, v[0:1]
	s_mov_b32 m0, s22
	s_nop 0
	global_load_lds_dwordx4 v[158:159], off
	v_lshl_add_u64 v[158:159], s[18:19], 0, v[154:155]
	s_add_i32 m0, s22, 0x2000
	s_nop 0
	global_load_lds_dwordx4 v[158:159], off
	v_lshl_add_u64 v[158:159], v[188:189], 0, s[82:83]
	s_mov_b32 m0, s36
	s_nop 0
	global_load_lds_dwordx4 v[158:159], off
	v_lshl_add_u64 v[158:159], v[218:219], 0, s[82:83]
	s_mov_b32 m0, s37
	s_nop 0
	global_load_lds_dwordx4 v[158:159], off
	s_waitcnt vmcnt(8)
	s_waitcnt lgkmcnt(0)
	s_barrier
	s_setprio 1
	v_mfma_f32_16x16x32_bf16 v[62:65], v[114:117], v[180:183], v[62:65]
	v_mfma_f32_16x16x32_bf16 v[58:61], v[122:125], v[180:183], v[58:61]
	v_mfma_f32_16x16x32_bf16 v[46:49], v[114:117], v[194:197], v[46:49]
	v_mfma_f32_16x16x32_bf16 v[42:45], v[122:125], v[194:197], v[42:45]
	v_mfma_f32_16x16x32_bf16 v[30:33], v[114:117], v[202:205], v[30:33]
	v_mfma_f32_16x16x32_bf16 v[26:29], v[122:125], v[202:205], v[26:29]
	v_mfma_f32_16x16x32_bf16 v[14:17], v[114:117], v[210:213], v[14:17]
	v_mfma_f32_16x16x32_bf16 v[10:13], v[122:125], v[210:213], v[10:13]
	v_mfma_f32_16x16x32_bf16 v[62:65], v[118:121], v[184:187], v[62:65]
	v_mfma_f32_16x16x32_bf16 v[58:61], v[134:137], v[184:187], v[58:61]
	v_mfma_f32_16x16x32_bf16 v[46:49], v[118:121], v[198:201], v[46:49]
	v_mfma_f32_16x16x32_bf16 v[42:45], v[134:137], v[198:201], v[42:45]
	v_mfma_f32_16x16x32_bf16 v[30:33], v[118:121], v[206:209], v[30:33]
	v_mfma_f32_16x16x32_bf16 v[26:29], v[134:137], v[206:209], v[26:29]
	v_mfma_f32_16x16x32_bf16 v[14:17], v[118:121], v[214:217], v[14:17]
	v_mfma_f32_16x16x32_bf16 v[10:13], v[134:137], v[214:217], v[10:13]
	s_setprio 0
	s_setprio 1
	v_mfma_f32_16x16x32_bf16 v[54:57], v[146:149], v[180:183], v[54:57]
	v_mfma_f32_16x16x32_bf16 v[50:53], v[172:175], v[180:183], v[50:53]
	v_mfma_f32_16x16x32_bf16 v[38:41], v[146:149], v[194:197], v[38:41]
	v_mfma_f32_16x16x32_bf16 v[34:37], v[172:175], v[194:197], v[34:37]
	v_mfma_f32_16x16x32_bf16 v[22:25], v[146:149], v[202:205], v[22:25]
	v_mfma_f32_16x16x32_bf16 v[18:21], v[172:175], v[202:205], v[18:21]
	v_mfma_f32_16x16x32_bf16 v[6:9], v[146:149], v[210:213], v[6:9]
	v_mfma_f32_16x16x32_bf16 v[2:5], v[172:175], v[210:213], v[2:5]
	v_mfma_f32_16x16x32_bf16 v[54:57], v[150:153], v[184:187], v[54:57]
	v_mfma_f32_16x16x32_bf16 v[50:53], v[176:179], v[184:187], v[50:53]
	v_mfma_f32_16x16x32_bf16 v[38:41], v[150:153], v[198:201], v[38:41]
	v_mfma_f32_16x16x32_bf16 v[34:37], v[176:179], v[198:201], v[34:37]
	v_mfma_f32_16x16x32_bf16 v[22:25], v[150:153], v[206:209], v[22:25]
	v_mfma_f32_16x16x32_bf16 v[18:21], v[176:179], v[206:209], v[18:21]
	v_mfma_f32_16x16x32_bf16 v[6:9], v[150:153], v[214:217], v[6:9]
	v_mfma_f32_16x16x32_bf16 v[2:5], v[176:179], v[214:217], v[2:5]
	s_setprio 0
	s_barrier
	s_add_i32 s45, s45, 2
	s_add_u32 s43, s43, 0x100
	s_addc_u32 s44, s44, 0
	s_cmp_gt_u32 s45, 41
	s_mov_b64 s[18:19], s[20:21]
	s_cbranch_scc0 .LBB0_966
	s_and_b64 vcc, exec, s[14:15]
	s_cbranch_vccz .LBB0_969
	s_barrier
